# v16 plus branch-free top-k candidate compaction (5 instead of 9 instructions per key; always write at slot min(cl,31), cl advances with the compare's carry)
# speedup vs baseline: 1.0007x; 1.0007x over previous
; #define LAS __attribute__((address_space(3)))
; template <int NCH>
; __device__ __forceinline__ void dsa_topk_query(unsigned char* ws, const float* srow  , LAS unsigned* hist  , int t, int lane_in) {
;     ...
;             for (int b = 31; b >= 0; --b) { const unsigned cand = Tl | (1u << b); int cnt = 0;
; #pragma unroll
;                 for (int j = 0; j < NG; ++j) asm volatile("v_cmp_ge_u32 vcc, %1, %2\n\tv_addc_co_u32 %0, vcc, 0, %0, vcc" : "+v"(cnt) : "v"(mx[j]), "v"(cand) : "vcc");
;                 cnt = wave_sum_i(cnt);
;                 if (cnt >= 256) { Tl = cand; if (cnt <= 256 + NCH / 2 - 16) break; } }
;             LAS unsigned* cb = hist;
;             int cl = 0;
; #pragma unroll
;             for (int c = 0; c < NCH; ++c) { const bool pr = u[c] >= Tl; if (pr) cb[((cl & 31) << 6) + lane] = u[c]; cl += pr ? 1 : 0; }
.LBB0_2299:
	v_lshlrev_b32_e64 v164, v163, 1
	v_mov_b32_e32 v165, 0
	v_or_b32_e32 v164, v164, v122
	v_cmp_ge_u32 vcc, v126, v164
	v_addc_co_u32 v165, vcc, 0, v165, vcc
	s_nop 0
	v_cmp_ge_u32 vcc, v131, v164
	v_addc_co_u32 v165, vcc, 0, v165, vcc
	s_nop 0
	v_cmp_ge_u32 vcc, v139, v164
	v_addc_co_u32 v165, vcc, 0, v165, vcc
	s_nop 0
	v_cmp_ge_u32 vcc, v142, v164
	v_addc_co_u32 v165, vcc, 0, v165, vcc
	s_nop 0
	v_cmp_ge_u32 vcc, v143, v164
	v_addc_co_u32 v165, vcc, 0, v165, vcc
	s_nop 0
	v_cmp_ge_u32 vcc, v144, v164
	v_addc_co_u32 v165, vcc, 0, v165, vcc
	s_nop 0
	v_cmp_ge_u32 vcc, v145, v164
	v_addc_co_u32 v165, vcc, 0, v165, vcc
	s_nop 0
	v_cmp_ge_u32 vcc, v146, v164
	v_addc_co_u32 v165, vcc, 0, v165, vcc
	s_nop 0
	v_cmp_ge_u32 vcc, v147, v164
	v_addc_co_u32 v165, vcc, 0, v165, vcc
	s_nop 0
	v_cmp_ge_u32 vcc, v156, v164
	v_addc_co_u32 v165, vcc, 0, v165, vcc
	s_nop 0
	v_cmp_ge_u32 vcc, v157, v164
	v_addc_co_u32 v165, vcc, 0, v165, vcc
	s_nop 0
	v_cmp_ge_u32 vcc, v158, v164
	v_addc_co_u32 v165, vcc, 0, v165, vcc
	s_nop 0
	v_cmp_ge_u32 vcc, v159, v164
	v_addc_co_u32 v165, vcc, 0, v165, vcc
	s_nop 0
	v_cmp_ge_u32 vcc, v160, v164
	v_addc_co_u32 v165, vcc, 0, v165, vcc
	s_nop 0
	v_cmp_ge_u32 vcc, v161, v164
	v_addc_co_u32 v165, vcc, 0, v165, vcc
	s_nop 0
	v_cmp_ge_u32 vcc, v162, v164
	v_addc_co_u32 v165, vcc, 0, v165, vcc
	s_nop 1
	v_add_u32_dpp v165, v165, v165 quad_perm:[1,0,3,2] row_mask:0xf bank_mask:0xf bound_ctrl:1
	s_nop 1
	v_add_u32_dpp v165, v165, v165 quad_perm:[2,3,0,1] row_mask:0xf bank_mask:0xf bound_ctrl:1
	s_nop 1
	v_add_u32_dpp v165, v165, v165 row_half_mirror row_mask:0xf bank_mask:0xf bound_ctrl:1
	s_nop 1
	v_add_u32_dpp v165, v165, v165 row_mirror row_mask:0xf bank_mask:0xf bound_ctrl:1
	s_nop 0
	v_readlane_b32 s0, v165, 0
	v_readlane_b32 s1, v165, 16
	s_add_i32 s0, s1, s0
	v_readlane_b32 s1, v165, 32
	s_add_i32 s0, s0, s1
	v_readlane_b32 s1, v165, 48
	s_add_i32 s0, s0, s1
	s_cmpk_lt_i32 s0, 0x100
	s_cselect_b64 vcc, -1, 0
	s_addk_i32 s0, 0xff00
	s_cmp_lt_u32 s0, 49
	v_cndmask_b32_e32 v122, v164, v122, vcc
	s_cselect_b64 s[0:1], -1, 0
	v_subrev_co_u32_e32 v163, vcc, 1, v163
	s_or_b64 s[0:1], s[0:1], vcc
	s_andn2_b64 vcc, exec, s[0:1]
	s_cbranch_vccnz .LBB0_2299
	v_lshl_add_u32 v126, v138, 2, s5
	v_cmp_ge_u32_e32 vcc, v128, v122
	v_mov_b32_e32 v131, 0
	s_and_saveexec_b64 s[0:1], vcc
	v_mov_b32_e32 v131, 64
	ds_write_b32 v126, v128
	s_or_b64 exec, exec, s[0:1]
	v_cmp_ge_u32_e64 s[0:1], v1, v122
	s_and_saveexec_b64 s[6:7], s[0:1]
	v_lshl_add_u32 v131, v131, 2, v126
	ds_write_b32 v131, v1
	s_or_b64 exec, exec, s[6:7]
	v_cndmask_b32_e64 v131, 0, 1, vcc
	v_cndmask_b32_e64 v139, 0, 1, s[0:1]
	v_add_u32_e32 v131, v131, v139
	v_cmp_ge_u32_e32 vcc, v140, v122
	s_and_saveexec_b64 s[0:1], vcc
	v_lshl_add_u32 v139, v131, 8, v126
	ds_write_b32 v139, v140
	s_or_b64 exec, exec, s[0:1]
	v_cndmask_b32_e64 v139, 0, 1, vcc
	v_add_u32_e32 v131, v131, v139
	v_cmp_ge_u32_e32 vcc, v129, v122
	s_and_saveexec_b64 s[0:1], vcc
	v_lshl_add_u32 v139, v131, 8, v126
	ds_write_b32 v139, v129
	s_or_b64 exec, exec, s[0:1]
	v_cndmask_b32_e64 v139, 0, 1, vcc
	v_add_u32_e32 v131, v131, v139
	v_cmp_ge_u32_e32 vcc, v130, v122
	s_and_saveexec_b64 s[0:1], vcc
	v_lshl_add_u32 v139, v131, 8, v126
	ds_write_b32 v139, v130
	s_or_b64 exec, exec, s[0:1]
	v_cndmask_b32_e64 v139, 0, 1, vcc
	v_add_u32_e32 v131, v131, v139
	v_cmp_ge_u32_e32 vcc, v125, v122
	s_and_saveexec_b64 s[0:1], vcc
	v_lshl_add_u32 v139, v131, 8, v126
	ds_write_b32 v139, v125
	s_or_b64 exec, exec, s[0:1]
	v_cndmask_b32_e64 v139, 0, 1, vcc
	v_add_u32_e32 v131, v131, v139
	v_cmp_ge_u32_e32 vcc, v124, v122
	v_min_u32_e32 v139, 31, v131
	v_lshl_add_u32 v139, v139, 8, v126
	ds_write_b32 v139, v124
	v_addc_co_u32_e32 v131, vcc, 0, v131, vcc
	v_cmp_ge_u32_e32 vcc, v127, v122
	v_min_u32_e32 v139, 31, v131
	v_lshl_add_u32 v139, v139, 8, v126
	ds_write_b32 v139, v127
	v_addc_co_u32_e32 v131, vcc, 0, v131, vcc
	v_cmp_ge_u32_e32 vcc, v2, v122
	v_min_u32_e32 v139, 31, v131
	v_lshl_add_u32 v139, v139, 8, v126
	ds_write_b32 v139, v2
	v_addc_co_u32_e32 v131, vcc, 0, v131, vcc
	v_cmp_ge_u32_e32 vcc, v121, v122
	v_min_u32_e32 v139, 31, v131
	v_lshl_add_u32 v139, v139, 8, v126
	ds_write_b32 v139, v121
	v_addc_co_u32_e32 v131, vcc, 0, v131, vcc
	v_cmp_ge_u32_e32 vcc, v120, v122
	v_min_u32_e32 v139, 31, v131
	v_lshl_add_u32 v139, v139, 8, v126
	ds_write_b32 v139, v120
	v_addc_co_u32_e32 v131, vcc, 0, v131, vcc
	v_cmp_ge_u32_e32 vcc, v123, v122
	v_min_u32_e32 v139, 31, v131
	v_lshl_add_u32 v139, v139, 8, v126
	ds_write_b32 v139, v123
	v_addc_co_u32_e32 v131, vcc, 0, v131, vcc
	v_cmp_ge_u32_e32 vcc, v116, v122
	v_min_u32_e32 v139, 31, v131
	v_lshl_add_u32 v139, v139, 8, v126
	ds_write_b32 v139, v116
	v_addc_co_u32_e32 v131, vcc, 0, v131, vcc
	v_cmp_ge_u32_e32 vcc, v117, v122
	v_min_u32_e32 v139, 31, v131
	v_lshl_add_u32 v139, v139, 8, v126
	ds_write_b32 v139, v117
	v_addc_co_u32_e32 v131, vcc, 0, v131, vcc
	v_cmp_ge_u32_e32 vcc, v118, v122
	v_min_u32_e32 v139, 31, v131
	v_lshl_add_u32 v139, v139, 8, v126
	ds_write_b32 v139, v118
	v_addc_co_u32_e32 v131, vcc, 0, v131, vcc
	v_cmp_ge_u32_e32 vcc, v119, v122
	v_min_u32_e32 v139, 31, v131
	v_lshl_add_u32 v139, v139, 8, v126
	ds_write_b32 v139, v119
	v_addc_co_u32_e32 v131, vcc, 0, v131, vcc
	v_cmp_ge_u32_e32 vcc, v112, v122
	v_min_u32_e32 v139, 31, v131
	v_lshl_add_u32 v139, v139, 8, v126
	ds_write_b32 v139, v112
	v_addc_co_u32_e32 v131, vcc, 0, v131, vcc
	v_cmp_ge_u32_e32 vcc, v113, v122
	v_min_u32_e32 v139, 31, v131
	v_lshl_add_u32 v139, v139, 8, v126
	ds_write_b32 v139, v113
	v_addc_co_u32_e32 v131, vcc, 0, v131, vcc
	v_cmp_ge_u32_e32 vcc, v114, v122
	v_min_u32_e32 v139, 31, v131
; template <int NCH>
; __device__ __forceinline__ void dsa_topk_query(unsigned char* ws, const float* srow  , LAS unsigned* hist  , int t, int lane_in) {
;     ...
;             int cl = 0;
; #pragma unroll
;             for (int c = 0; c < NCH; ++c) { const bool pr = u[c] >= Tl; if (pr) cb[((cl & 31) << 6) + lane] = u[c]; cl += pr ? 1 : 0; }
	v_lshl_add_u32 v139, v139, 8, v126
	ds_write_b32 v139, v114
	v_addc_co_u32_e32 v131, vcc, 0, v131, vcc
	v_cmp_ge_u32_e32 vcc, v115, v122
	v_min_u32_e32 v139, 31, v131
	v_lshl_add_u32 v139, v139, 8, v126
	ds_write_b32 v139, v115
	v_addc_co_u32_e32 v131, vcc, 0, v131, vcc
	v_cmp_ge_u32_e32 vcc, v108, v122
	v_min_u32_e32 v139, 31, v131
	v_lshl_add_u32 v139, v139, 8, v126
	ds_write_b32 v139, v108
	v_addc_co_u32_e32 v131, vcc, 0, v131, vcc
	v_cmp_ge_u32_e32 vcc, v109, v122
	v_min_u32_e32 v139, 31, v131
	v_lshl_add_u32 v139, v139, 8, v126
	ds_write_b32 v139, v109
	v_addc_co_u32_e32 v131, vcc, 0, v131, vcc
	v_cmp_ge_u32_e32 vcc, v110, v122
	v_min_u32_e32 v139, 31, v131
	v_lshl_add_u32 v139, v139, 8, v126
	ds_write_b32 v139, v110
	v_addc_co_u32_e32 v131, vcc, 0, v131, vcc
	v_cmp_ge_u32_e32 vcc, v111, v122
	v_min_u32_e32 v139, 31, v131
	v_lshl_add_u32 v139, v139, 8, v126
	ds_write_b32 v139, v111
	v_addc_co_u32_e32 v131, vcc, 0, v131, vcc
	v_cmp_ge_u32_e32 vcc, v104, v122
	v_min_u32_e32 v139, 31, v131
	v_lshl_add_u32 v139, v139, 8, v126
	ds_write_b32 v139, v104
	v_addc_co_u32_e32 v131, vcc, 0, v131, vcc
	v_cmp_ge_u32_e32 vcc, v105, v122
	v_min_u32_e32 v139, 31, v131
	v_lshl_add_u32 v139, v139, 8, v126
	ds_write_b32 v139, v105
	v_addc_co_u32_e32 v131, vcc, 0, v131, vcc
	v_cmp_ge_u32_e32 vcc, v106, v122
	v_min_u32_e32 v139, 31, v131
	v_lshl_add_u32 v139, v139, 8, v126
	ds_write_b32 v139, v106
	v_addc_co_u32_e32 v131, vcc, 0, v131, vcc
	v_cmp_ge_u32_e32 vcc, v107, v122
	v_min_u32_e32 v139, 31, v131
	v_lshl_add_u32 v139, v139, 8, v126
	ds_write_b32 v139, v107
	v_addc_co_u32_e32 v131, vcc, 0, v131, vcc
	v_cmp_ge_u32_e32 vcc, v100, v122
	v_min_u32_e32 v139, 31, v131
	v_lshl_add_u32 v139, v139, 8, v126
	ds_write_b32 v139, v100
	v_addc_co_u32_e32 v131, vcc, 0, v131, vcc
	v_cmp_ge_u32_e32 vcc, v101, v122
	v_min_u32_e32 v139, 31, v131
	v_lshl_add_u32 v139, v139, 8, v126
	ds_write_b32 v139, v101
	v_addc_co_u32_e32 v131, vcc, 0, v131, vcc
	v_cmp_ge_u32_e32 vcc, v102, v122
	v_min_u32_e32 v139, 31, v131
	v_lshl_add_u32 v139, v139, 8, v126
	ds_write_b32 v139, v102
	v_addc_co_u32_e32 v131, vcc, 0, v131, vcc
	v_cmp_ge_u32_e32 vcc, v103, v122
	v_min_u32_e32 v139, 31, v131
	v_lshl_add_u32 v139, v139, 8, v126
	ds_write_b32 v139, v103
	v_addc_co_u32_e32 v131, vcc, 0, v131, vcc
	v_cmp_ge_u32_e32 vcc, v96, v122
	v_min_u32_e32 v139, 31, v131
	v_lshl_add_u32 v139, v139, 8, v126
	ds_write_b32 v139, v96
	v_addc_co_u32_e32 v131, vcc, 0, v131, vcc
	v_cmp_ge_u32_e32 vcc, v97, v122
	v_min_u32_e32 v139, 31, v131
	v_lshl_add_u32 v139, v139, 8, v126
	ds_write_b32 v139, v97
	v_addc_co_u32_e32 v131, vcc, 0, v131, vcc
	v_cmp_ge_u32_e32 vcc, v98, v122
	v_min_u32_e32 v139, 31, v131
	v_lshl_add_u32 v139, v139, 8, v126
	ds_write_b32 v139, v98
	v_addc_co_u32_e32 v131, vcc, 0, v131, vcc
	v_cmp_ge_u32_e32 vcc, v99, v122
	v_min_u32_e32 v139, 31, v131
	v_lshl_add_u32 v139, v139, 8, v126
	ds_write_b32 v139, v99
	v_addc_co_u32_e32 v131, vcc, 0, v131, vcc
	v_cmp_ge_u32_e32 vcc, v92, v122
	v_min_u32_e32 v139, 31, v131
	v_lshl_add_u32 v139, v139, 8, v126
	ds_write_b32 v139, v92
	v_addc_co_u32_e32 v131, vcc, 0, v131, vcc
	v_cmp_ge_u32_e32 vcc, v93, v122
	v_min_u32_e32 v139, 31, v131
	v_lshl_add_u32 v139, v139, 8, v126
	ds_write_b32 v139, v93
	v_addc_co_u32_e32 v131, vcc, 0, v131, vcc
	v_cmp_ge_u32_e32 vcc, v94, v122
	v_min_u32_e32 v139, 31, v131
	v_lshl_add_u32 v139, v139, 8, v126
	ds_write_b32 v139, v94
	v_addc_co_u32_e32 v131, vcc, 0, v131, vcc
	v_cmp_ge_u32_e32 vcc, v95, v122
	v_min_u32_e32 v139, 31, v131
	v_lshl_add_u32 v139, v139, 8, v126
	ds_write_b32 v139, v95
	v_addc_co_u32_e32 v131, vcc, 0, v131, vcc
	v_cmp_ge_u32_e32 vcc, v88, v122
	v_min_u32_e32 v139, 31, v131
	v_lshl_add_u32 v139, v139, 8, v126
	ds_write_b32 v139, v88
	v_addc_co_u32_e32 v131, vcc, 0, v131, vcc
	v_cmp_ge_u32_e32 vcc, v89, v122
	v_min_u32_e32 v139, 31, v131
	v_lshl_add_u32 v139, v139, 8, v126
	ds_write_b32 v139, v89
	v_addc_co_u32_e32 v131, vcc, 0, v131, vcc
	v_cmp_ge_u32_e32 vcc, v90, v122
	v_min_u32_e32 v139, 31, v131
	v_lshl_add_u32 v139, v139, 8, v126
	ds_write_b32 v139, v90
	v_addc_co_u32_e32 v131, vcc, 0, v131, vcc
	v_cmp_ge_u32_e32 vcc, v91, v122
	v_min_u32_e32 v139, 31, v131
	v_lshl_add_u32 v139, v139, 8, v126
	ds_write_b32 v139, v91
	v_addc_co_u32_e32 v131, vcc, 0, v131, vcc
	v_cmp_ge_u32_e32 vcc, v84, v122
	v_min_u32_e32 v139, 31, v131
	v_lshl_add_u32 v139, v139, 8, v126
	ds_write_b32 v139, v84
	v_addc_co_u32_e32 v131, vcc, 0, v131, vcc
	v_cmp_ge_u32_e32 vcc, v85, v122
	v_min_u32_e32 v139, 31, v131
	v_lshl_add_u32 v139, v139, 8, v126
	ds_write_b32 v139, v85
	v_addc_co_u32_e32 v131, vcc, 0, v131, vcc
	v_cmp_ge_u32_e32 vcc, v86, v122
	v_min_u32_e32 v139, 31, v131
	v_lshl_add_u32 v139, v139, 8, v126
	ds_write_b32 v139, v86
	v_addc_co_u32_e32 v131, vcc, 0, v131, vcc
	v_cmp_ge_u32_e32 vcc, v87, v122
	v_min_u32_e32 v139, 31, v131
	v_lshl_add_u32 v139, v139, 8, v126
	ds_write_b32 v139, v87
	v_addc_co_u32_e32 v131, vcc, 0, v131, vcc
	v_cmp_ge_u32_e32 vcc, v80, v122
	v_min_u32_e32 v139, 31, v131
	v_lshl_add_u32 v139, v139, 8, v126
	ds_write_b32 v139, v80
	v_addc_co_u32_e32 v131, vcc, 0, v131, vcc
	v_cmp_ge_u32_e32 vcc, v81, v122
	v_min_u32_e32 v139, 31, v131
	v_lshl_add_u32 v139, v139, 8, v126
	ds_write_b32 v139, v81
	v_addc_co_u32_e32 v131, vcc, 0, v131, vcc
	v_cmp_ge_u32_e32 vcc, v82, v122
	v_min_u32_e32 v139, 31, v131
	v_lshl_add_u32 v139, v139, 8, v126
	ds_write_b32 v139, v82
	v_addc_co_u32_e32 v131, vcc, 0, v131, vcc
	v_cmp_ge_u32_e32 vcc, v83, v122
	v_min_u32_e32 v139, 31, v131
	v_lshl_add_u32 v139, v139, 8, v126
	ds_write_b32 v139, v83
	v_addc_co_u32_e32 v131, vcc, 0, v131, vcc
	v_cmp_ge_u32_e32 vcc, v76, v122
; #define LAS __attribute__((address_space(3)))
; template <int NCH>
; __device__ __forceinline__ void dsa_topk_query(unsigned char* ws, const float* srow  , LAS unsigned* hist  , int t, int lane_in) {
;     ...
;             LAS unsigned* cb = hist;
;             int cl = 0;
; #pragma unroll
;             for (int c = 0; c < NCH; ++c) { const bool pr = u[c] >= Tl; if (pr) cb[((cl & 31) << 6) + lane] = u[c]; cl += pr ? 1 : 0; }
	v_min_u32_e32 v139, 31, v131
	v_lshl_add_u32 v139, v139, 8, v126
	ds_write_b32 v139, v76
	v_addc_co_u32_e32 v131, vcc, 0, v131, vcc
	v_cmp_ge_u32_e32 vcc, v77, v122
	v_min_u32_e32 v139, 31, v131
	v_lshl_add_u32 v139, v139, 8, v126
	ds_write_b32 v139, v77
	v_addc_co_u32_e32 v131, vcc, 0, v131, vcc
	v_cmp_ge_u32_e32 vcc, v78, v122
	v_min_u32_e32 v139, 31, v131
	v_lshl_add_u32 v139, v139, 8, v126
	ds_write_b32 v139, v78
	v_addc_co_u32_e32 v131, vcc, 0, v131, vcc
	v_cmp_ge_u32_e32 vcc, v79, v122
	v_min_u32_e32 v139, 31, v131
	v_lshl_add_u32 v139, v139, 8, v126
	ds_write_b32 v139, v79
	v_addc_co_u32_e32 v131, vcc, 0, v131, vcc
	v_cmp_ge_u32_e32 vcc, v72, v122
	v_min_u32_e32 v139, 31, v131
	v_lshl_add_u32 v139, v139, 8, v126
	ds_write_b32 v139, v72
	v_addc_co_u32_e32 v131, vcc, 0, v131, vcc
	v_cmp_ge_u32_e32 vcc, v73, v122
	v_min_u32_e32 v139, 31, v131
	v_lshl_add_u32 v139, v139, 8, v126
	ds_write_b32 v139, v73
	v_addc_co_u32_e32 v131, vcc, 0, v131, vcc
	v_cmp_ge_u32_e32 vcc, v74, v122
	v_min_u32_e32 v139, 31, v131
	v_lshl_add_u32 v139, v139, 8, v126
	ds_write_b32 v139, v74
	v_addc_co_u32_e32 v131, vcc, 0, v131, vcc
	v_cmp_ge_u32_e32 vcc, v75, v122
	v_min_u32_e32 v139, 31, v131
	v_lshl_add_u32 v139, v139, 8, v126
	ds_write_b32 v139, v75
	v_addc_co_u32_e32 v131, vcc, 0, v131, vcc
	v_cmp_ge_u32_e32 vcc, v68, v122
	v_min_u32_e32 v139, 31, v131
	v_lshl_add_u32 v139, v139, 8, v126
	ds_write_b32 v139, v68
	v_addc_co_u32_e32 v131, vcc, 0, v131, vcc
	v_cmp_ge_u32_e32 vcc, v69, v122
	v_min_u32_e32 v139, 31, v131
	v_lshl_add_u32 v139, v139, 8, v126
	ds_write_b32 v139, v69
	v_addc_co_u32_e32 v131, vcc, 0, v131, vcc
	v_cmp_ge_u32_e32 vcc, v70, v122
	v_min_u32_e32 v139, 31, v131
	v_lshl_add_u32 v139, v139, 8, v126
	ds_write_b32 v139, v70
	v_addc_co_u32_e32 v131, vcc, 0, v131, vcc
	v_cmp_ge_u32_e32 vcc, v71, v122
	v_min_u32_e32 v139, 31, v131
	v_lshl_add_u32 v139, v139, 8, v126
	ds_write_b32 v139, v71
	v_addc_co_u32_e32 v131, vcc, 0, v131, vcc
	v_cmp_ge_u32_e32 vcc, v64, v122
	v_min_u32_e32 v139, 31, v131
	v_lshl_add_u32 v139, v139, 8, v126
	ds_write_b32 v139, v64
	v_addc_co_u32_e32 v131, vcc, 0, v131, vcc
	v_cmp_ge_u32_e32 vcc, v65, v122
	v_min_u32_e32 v139, 31, v131
	v_lshl_add_u32 v139, v139, 8, v126
	ds_write_b32 v139, v65
	v_addc_co_u32_e32 v131, vcc, 0, v131, vcc
	v_cmp_ge_u32_e32 vcc, v66, v122
	v_min_u32_e32 v139, 31, v131
	v_lshl_add_u32 v139, v139, 8, v126
	ds_write_b32 v139, v66
	v_addc_co_u32_e32 v131, vcc, 0, v131, vcc
	v_cmp_ge_u32_e32 vcc, v67, v122
	v_min_u32_e32 v139, 31, v131
	v_lshl_add_u32 v139, v139, 8, v126
	ds_write_b32 v139, v67
	v_addc_co_u32_e32 v131, vcc, 0, v131, vcc
	v_cmp_ge_u32_e32 vcc, v60, v122
	v_min_u32_e32 v139, 31, v131
	v_lshl_add_u32 v139, v139, 8, v126
	ds_write_b32 v139, v60
	v_addc_co_u32_e32 v131, vcc, 0, v131, vcc
	v_cmp_ge_u32_e32 vcc, v61, v122
	v_min_u32_e32 v139, 31, v131
	v_lshl_add_u32 v139, v139, 8, v126
	ds_write_b32 v139, v61
	v_addc_co_u32_e32 v131, vcc, 0, v131, vcc
	v_cmp_ge_u32_e32 vcc, v62, v122
	v_min_u32_e32 v139, 31, v131
	v_lshl_add_u32 v139, v139, 8, v126
	ds_write_b32 v139, v62
	v_addc_co_u32_e32 v131, vcc, 0, v131, vcc
	v_cmp_ge_u32_e32 vcc, v63, v122
	v_min_u32_e32 v139, 31, v131
	v_lshl_add_u32 v139, v139, 8, v126
	ds_write_b32 v139, v63
	v_addc_co_u32_e32 v131, vcc, 0, v131, vcc
	v_cmp_ge_u32_e32 vcc, v56, v122
	v_min_u32_e32 v139, 31, v131
	v_lshl_add_u32 v139, v139, 8, v126
	ds_write_b32 v139, v56
	v_addc_co_u32_e32 v131, vcc, 0, v131, vcc
	v_cmp_ge_u32_e32 vcc, v57, v122
	v_min_u32_e32 v139, 31, v131
	v_lshl_add_u32 v139, v139, 8, v126
	ds_write_b32 v139, v57
	v_addc_co_u32_e32 v131, vcc, 0, v131, vcc
	v_cmp_ge_u32_e32 vcc, v58, v122
	v_min_u32_e32 v139, 31, v131
	v_lshl_add_u32 v139, v139, 8, v126
	ds_write_b32 v139, v58
	v_addc_co_u32_e32 v131, vcc, 0, v131, vcc
	v_cmp_ge_u32_e32 vcc, v59, v122
	v_min_u32_e32 v139, 31, v131
	v_lshl_add_u32 v139, v139, 8, v126
	ds_write_b32 v139, v59
	v_addc_co_u32_e32 v131, vcc, 0, v131, vcc
	v_cmp_ge_u32_e32 vcc, v52, v122
	v_min_u32_e32 v139, 31, v131
	v_lshl_add_u32 v139, v139, 8, v126
	ds_write_b32 v139, v52
	v_addc_co_u32_e32 v131, vcc, 0, v131, vcc
	v_cmp_ge_u32_e32 vcc, v53, v122
	v_min_u32_e32 v139, 31, v131
	v_lshl_add_u32 v139, v139, 8, v126
	ds_write_b32 v139, v53
	v_addc_co_u32_e32 v131, vcc, 0, v131, vcc
	v_cmp_ge_u32_e32 vcc, v54, v122
	v_min_u32_e32 v139, 31, v131
	v_lshl_add_u32 v139, v139, 8, v126
	ds_write_b32 v139, v54
	v_addc_co_u32_e32 v131, vcc, 0, v131, vcc
	v_cmp_ge_u32_e32 vcc, v55, v122
	v_min_u32_e32 v139, 31, v131
	v_lshl_add_u32 v139, v139, 8, v126
	ds_write_b32 v139, v55
	v_addc_co_u32_e32 v131, vcc, 0, v131, vcc
	v_cmp_ge_u32_e32 vcc, v48, v122
	v_min_u32_e32 v139, 31, v131
	v_lshl_add_u32 v139, v139, 8, v126
	ds_write_b32 v139, v48
	v_addc_co_u32_e32 v131, vcc, 0, v131, vcc
	v_cmp_ge_u32_e32 vcc, v49, v122
	v_min_u32_e32 v139, 31, v131
	v_lshl_add_u32 v139, v139, 8, v126
	ds_write_b32 v139, v49
	v_addc_co_u32_e32 v131, vcc, 0, v131, vcc
	v_cmp_ge_u32_e32 vcc, v50, v122
	v_min_u32_e32 v139, 31, v131
	v_lshl_add_u32 v139, v139, 8, v126
	ds_write_b32 v139, v50
	v_addc_co_u32_e32 v131, vcc, 0, v131, vcc
	v_cmp_ge_u32_e32 vcc, v51, v122
	v_min_u32_e32 v139, 31, v131
	v_lshl_add_u32 v139, v139, 8, v126
	ds_write_b32 v139, v51
	v_addc_co_u32_e32 v131, vcc, 0, v131, vcc
	v_cmp_ge_u32_e32 vcc, v44, v122
	v_min_u32_e32 v139, 31, v131
	v_lshl_add_u32 v139, v139, 8, v126
	ds_write_b32 v139, v44
	v_addc_co_u32_e32 v131, vcc, 0, v131, vcc
	v_cmp_ge_u32_e32 vcc, v45, v122
	v_min_u32_e32 v139, 31, v131
	v_lshl_add_u32 v139, v139, 8, v126
	ds_write_b32 v139, v45
	v_addc_co_u32_e32 v131, vcc, 0, v131, vcc
	v_cmp_ge_u32_e32 vcc, v46, v122
; template <int NCH>
; __device__ __forceinline__ void dsa_topk_query(unsigned char* ws, const float* srow  , LAS unsigned* hist  , int t, int lane_in) {
;     ...
;             for (int c = 0; c < NCH; ++c) { const bool pr = u[c] >= Tl; if (pr) cb[((cl & 31) << 6) + lane] = u[c]; cl += pr ? 1 : 0; }
	v_min_u32_e32 v139, 31, v131
	v_lshl_add_u32 v139, v139, 8, v126
	ds_write_b32 v139, v46
	v_addc_co_u32_e32 v131, vcc, 0, v131, vcc
	v_cmp_ge_u32_e32 vcc, v47, v122
	v_min_u32_e32 v139, 31, v131
	v_lshl_add_u32 v139, v139, 8, v126
	ds_write_b32 v139, v47
	v_addc_co_u32_e32 v131, vcc, 0, v131, vcc
	v_cmp_ge_u32_e32 vcc, v40, v122
	v_min_u32_e32 v139, 31, v131
	v_lshl_add_u32 v139, v139, 8, v126
	ds_write_b32 v139, v40
	v_addc_co_u32_e32 v131, vcc, 0, v131, vcc
	v_cmp_ge_u32_e32 vcc, v41, v122
	v_min_u32_e32 v139, 31, v131
	v_lshl_add_u32 v139, v139, 8, v126
	ds_write_b32 v139, v41
	v_addc_co_u32_e32 v131, vcc, 0, v131, vcc
	v_cmp_ge_u32_e32 vcc, v42, v122
	v_min_u32_e32 v139, 31, v131
	v_lshl_add_u32 v139, v139, 8, v126
	ds_write_b32 v139, v42
	v_addc_co_u32_e32 v131, vcc, 0, v131, vcc
	v_cmp_ge_u32_e32 vcc, v43, v122
	v_min_u32_e32 v139, 31, v131
	v_lshl_add_u32 v139, v139, 8, v126
	ds_write_b32 v139, v43
	v_addc_co_u32_e32 v131, vcc, 0, v131, vcc
	v_cmp_ge_u32_e32 vcc, v36, v122
	v_min_u32_e32 v139, 31, v131
	v_lshl_add_u32 v139, v139, 8, v126
	ds_write_b32 v139, v36
	v_addc_co_u32_e32 v131, vcc, 0, v131, vcc
	v_cmp_ge_u32_e32 vcc, v37, v122
	v_min_u32_e32 v139, 31, v131
	v_lshl_add_u32 v139, v139, 8, v126
	ds_write_b32 v139, v37
	v_addc_co_u32_e32 v131, vcc, 0, v131, vcc
	v_cmp_ge_u32_e32 vcc, v38, v122
	v_min_u32_e32 v139, 31, v131
	v_lshl_add_u32 v139, v139, 8, v126
	ds_write_b32 v139, v38
	v_addc_co_u32_e32 v131, vcc, 0, v131, vcc
	v_cmp_ge_u32_e32 vcc, v39, v122
	v_min_u32_e32 v139, 31, v131
	v_lshl_add_u32 v139, v139, 8, v126
	ds_write_b32 v139, v39
	v_addc_co_u32_e32 v131, vcc, 0, v131, vcc
	v_cmp_ge_u32_e32 vcc, v28, v122
	v_min_u32_e32 v139, 31, v131
	v_lshl_add_u32 v139, v139, 8, v126
	ds_write_b32 v139, v28
	v_addc_co_u32_e32 v131, vcc, 0, v131, vcc
	v_cmp_ge_u32_e32 vcc, v29, v122
	v_min_u32_e32 v139, 31, v131
	v_lshl_add_u32 v139, v139, 8, v126
	ds_write_b32 v139, v29
	v_addc_co_u32_e32 v131, vcc, 0, v131, vcc
	v_cmp_ge_u32_e32 vcc, v30, v122
	v_min_u32_e32 v139, 31, v131
	v_lshl_add_u32 v139, v139, 8, v126
	ds_write_b32 v139, v30
	v_addc_co_u32_e32 v131, vcc, 0, v131, vcc
	v_cmp_ge_u32_e32 vcc, v31, v122
	v_min_u32_e32 v139, 31, v131
	v_lshl_add_u32 v139, v139, 8, v126
	ds_write_b32 v139, v31
	v_addc_co_u32_e32 v131, vcc, 0, v131, vcc
	v_cmp_ge_u32_e32 vcc, v24, v122
	v_min_u32_e32 v139, 31, v131
	v_lshl_add_u32 v139, v139, 8, v126
	ds_write_b32 v139, v24
	v_addc_co_u32_e32 v131, vcc, 0, v131, vcc
	v_cmp_ge_u32_e32 vcc, v25, v122
	v_min_u32_e32 v139, 31, v131
	v_lshl_add_u32 v139, v139, 8, v126
	ds_write_b32 v139, v25
	v_addc_co_u32_e32 v131, vcc, 0, v131, vcc
	v_cmp_ge_u32_e32 vcc, v26, v122
	v_min_u32_e32 v139, 31, v131
	v_lshl_add_u32 v139, v139, 8, v126
	ds_write_b32 v139, v26
	v_addc_co_u32_e32 v131, vcc, 0, v131, vcc
	v_cmp_ge_u32_e32 vcc, v27, v122
	v_min_u32_e32 v139, 31, v131
	v_lshl_add_u32 v139, v139, 8, v126
	ds_write_b32 v139, v27
	v_addc_co_u32_e32 v131, vcc, 0, v131, vcc
	v_cmp_ge_u32_e32 vcc, v16, v122
	v_min_u32_e32 v139, 31, v131
	v_lshl_add_u32 v139, v139, 8, v126
	ds_write_b32 v139, v16
	v_addc_co_u32_e32 v131, vcc, 0, v131, vcc
	v_cmp_ge_u32_e32 vcc, v17, v122
	v_min_u32_e32 v139, 31, v131
	v_lshl_add_u32 v139, v139, 8, v126
	ds_write_b32 v139, v17
	v_addc_co_u32_e32 v131, vcc, 0, v131, vcc
	v_cmp_ge_u32_e32 vcc, v18, v122
	v_min_u32_e32 v139, 31, v131
	v_lshl_add_u32 v139, v139, 8, v126
	ds_write_b32 v139, v18
	v_addc_co_u32_e32 v131, vcc, 0, v131, vcc
	v_cmp_ge_u32_e32 vcc, v19, v122
	v_min_u32_e32 v139, 31, v131
	v_lshl_add_u32 v139, v139, 8, v126
	ds_write_b32 v139, v19
	v_addc_co_u32_e32 v131, vcc, 0, v131, vcc
	v_cmp_ge_u32_e32 vcc, v8, v122
	v_min_u32_e32 v139, 31, v131
	v_lshl_add_u32 v139, v139, 8, v126
	ds_write_b32 v139, v8
	v_addc_co_u32_e32 v131, vcc, 0, v131, vcc
	v_cmp_ge_u32_e32 vcc, v9, v122
	v_min_u32_e32 v139, 31, v131
	v_lshl_add_u32 v139, v139, 8, v126
	ds_write_b32 v139, v9
	v_addc_co_u32_e32 v131, vcc, 0, v131, vcc
	v_cmp_ge_u32_e32 vcc, v10, v122
	v_min_u32_e32 v139, 31, v131
	v_lshl_add_u32 v139, v139, 8, v126
	ds_write_b32 v139, v10
	v_addc_co_u32_e32 v131, vcc, 0, v131, vcc
	v_cmp_ge_u32_e32 vcc, v11, v122
	v_min_u32_e32 v139, 31, v131
	v_lshl_add_u32 v139, v139, 8, v126
	ds_write_b32 v139, v11
	v_addc_co_u32_e32 v131, vcc, 0, v131, vcc
	v_cmp_ge_u32_e32 vcc, v32, v122
	v_min_u32_e32 v139, 31, v131
	v_lshl_add_u32 v139, v139, 8, v126
	ds_write_b32 v139, v32
	v_addc_co_u32_e32 v131, vcc, 0, v131, vcc
	v_cmp_ge_u32_e32 vcc, v33, v122
	v_min_u32_e32 v139, 31, v131
	v_lshl_add_u32 v139, v139, 8, v126
	ds_write_b32 v139, v33
	v_addc_co_u32_e32 v131, vcc, 0, v131, vcc
	v_cmp_ge_u32_e32 vcc, v34, v122
	v_min_u32_e32 v139, 31, v131
	v_lshl_add_u32 v139, v139, 8, v126
	ds_write_b32 v139, v34
	v_addc_co_u32_e32 v131, vcc, 0, v131, vcc
	v_cmp_ge_u32_e32 vcc, v35, v122
	v_min_u32_e32 v139, 31, v131
	v_lshl_add_u32 v139, v139, 8, v126
	ds_write_b32 v139, v35
	v_addc_co_u32_e32 v131, vcc, 0, v131, vcc
	v_cmp_ge_u32_e32 vcc, v20, v122
	v_min_u32_e32 v139, 31, v131
	v_lshl_add_u32 v139, v139, 8, v126
	ds_write_b32 v139, v20
	v_addc_co_u32_e32 v131, vcc, 0, v131, vcc
; template <int NCH>
; __device__ __forceinline__ void dsa_topk_query(unsigned char* ws, const float* srow  , LAS unsigned* hist  , int t, int lane_in) {
;     ...
;             for (int c = 0; c < NCH; ++c) { const bool pr = u[c] >= Tl; if (pr) cb[((cl & 31) << 6) + lane] = u[c]; cl += pr ? 1 : 0; }
;             if (wave_max_i(cl) <= 16) {
;                 unsigned k[16];
; #pragma unroll
;                 for (int i = 0; i < 16; ++i) { k[i] = 0u; if (i < cl) k[i] = cb[(i << 6) + lane]; }
	v_cmp_ge_u32_e32 vcc, v21, v122
	v_min_u32_e32 v139, 31, v131
	v_lshl_add_u32 v139, v139, 8, v126
	ds_write_b32 v139, v21
	v_addc_co_u32_e32 v131, vcc, 0, v131, vcc
	v_cmp_ge_u32_e32 vcc, v22, v122
	v_min_u32_e32 v139, 31, v131
	v_lshl_add_u32 v139, v139, 8, v126
	ds_write_b32 v139, v22
	v_addc_co_u32_e32 v131, vcc, 0, v131, vcc
	v_cmp_ge_u32_e32 vcc, v23, v122
	v_min_u32_e32 v139, 31, v131
	v_lshl_add_u32 v139, v139, 8, v126
	ds_write_b32 v139, v23
	v_addc_co_u32_e32 v131, vcc, 0, v131, vcc
	v_cmp_ge_u32_e32 vcc, v12, v122
	v_min_u32_e32 v139, 31, v131
	v_lshl_add_u32 v139, v139, 8, v126
	ds_write_b32 v139, v12
	v_addc_co_u32_e32 v131, vcc, 0, v131, vcc
	v_cmp_ge_u32_e32 vcc, v13, v122
	v_min_u32_e32 v139, 31, v131
	v_lshl_add_u32 v139, v139, 8, v126
	ds_write_b32 v139, v13
	v_addc_co_u32_e32 v131, vcc, 0, v131, vcc
	v_cmp_ge_u32_e32 vcc, v14, v122
	v_min_u32_e32 v139, 31, v131
	v_lshl_add_u32 v139, v139, 8, v126
	ds_write_b32 v139, v14
	v_addc_co_u32_e32 v131, vcc, 0, v131, vcc
	v_cmp_ge_u32_e32 vcc, v15, v122
	v_min_u32_e32 v139, 31, v131
	v_lshl_add_u32 v139, v139, 8, v126
	ds_write_b32 v139, v15
	v_addc_co_u32_e32 v131, vcc, 0, v131, vcc
	v_cmp_ge_u32_e32 vcc, v4, v122
	v_min_u32_e32 v139, 31, v131
	v_lshl_add_u32 v139, v139, 8, v126
	ds_write_b32 v139, v4
	v_addc_co_u32_e32 v131, vcc, 0, v131, vcc
	v_cmp_ge_u32_e32 vcc, v5, v122
	v_min_u32_e32 v139, 31, v131
	v_lshl_add_u32 v139, v139, 8, v126
	ds_write_b32 v139, v5
	v_addc_co_u32_e32 v131, vcc, 0, v131, vcc
	v_cmp_ge_u32_e32 vcc, v6, v122
	v_min_u32_e32 v139, 31, v131
	v_lshl_add_u32 v139, v139, 8, v126
	ds_write_b32 v139, v6
	v_addc_co_u32_e32 v131, vcc, 0, v131, vcc
	v_cmp_ge_u32_e32 vcc, v7, v122
	s_and_saveexec_b64 s[0:1], vcc
	v_lshlrev_b32_e32 v139, 8, v131
	v_and_b32_e32 v139, 0x1f00, v139
	v_add_u32_e32 v139, v126, v139
	ds_write_b32 v139, v7
	s_or_b64 exec, exec, s[0:1]
	v_cndmask_b32_e64 v139, 0, 1, vcc
	v_add_u32_e32 v164, v131, v139
	s_mov_b32 s10, 0
	s_nop 0
	v_max_i32_dpp v131, v164, v164 quad_perm:[1,0,3,2] row_mask:0xf bank_mask:0xf bound_ctrl:1
	s_nop 1
	v_max_i32_dpp v131, v131, v131 quad_perm:[2,3,0,1] row_mask:0xf bank_mask:0xf bound_ctrl:1
	s_nop 1
	v_max_i32_dpp v131, v131, v131 row_half_mirror row_mask:0xf bank_mask:0xf bound_ctrl:1
	s_nop 1
	v_max_i32_dpp v131, v131, v131 row_mirror row_mask:0xf bank_mask:0xf bound_ctrl:1
	s_nop 0
	v_readlane_b32 s2, v131, 32
	v_readlane_b32 s6, v131, 48
	v_readlane_b32 s1, v131, 16
	s_max_i32 s2, s2, s6
	v_readlane_b32 s0, v131, 0
	v_mov_b32_e32 v131, s1
	v_mov_b32_e32 v139, s2
	v_max3_i32 v131, s0, v131, v139
	v_cmp_lt_i32_e64 s[0:1], 16, v131
	s_and_b64 vcc, exec, s[0:1]
	s_cbranch_vccnz .LBB0_2593
	v_mov_b32_e32 v131, 0
	v_cmp_ne_u32_e32 vcc, 0, v164
	v_mov_b32_e32 v139, 0
	s_and_saveexec_b64 s[6:7], vcc
	ds_read_b32 v139, v126
	s_or_b64 exec, exec, s[6:7]
	v_cmp_lt_u32_e32 vcc, 1, v164
	s_and_saveexec_b64 s[6:7], vcc
	ds_read_b32 v131, v126 offset:256
	s_or_b64 exec, exec, s[6:7]
	v_cmp_lt_u32_e32 vcc, 2, v164
	v_mov_b32_e32 v142, 0
	v_mov_b32_e32 v143, 0
	s_and_saveexec_b64 s[6:7], vcc
	ds_read_b32 v143, v126 offset:512
	s_or_b64 exec, exec, s[6:7]
	v_cmp_lt_u32_e32 vcc, 3, v164
	s_and_saveexec_b64 s[6:7], vcc
	ds_read_b32 v142, v126 offset:768
	s_or_b64 exec, exec, s[6:7]
	v_cmp_lt_u32_e32 vcc, 4, v164
	v_mov_b32_e32 v144, 0
	v_mov_b32_e32 v145, 0
	s_and_saveexec_b64 s[6:7], vcc
	ds_read_b32 v145, v126 offset:1024
	s_or_b64 exec, exec, s[6:7]
	v_cmp_lt_u32_e32 vcc, 5, v164
	s_and_saveexec_b64 s[6:7], vcc
	ds_read_b32 v144, v126 offset:1280
	s_or_b64 exec, exec, s[6:7]
	v_cmp_lt_u32_e32 vcc, 6, v164
	v_mov_b32_e32 v146, 0
	v_mov_b32_e32 v147, 0
	s_and_saveexec_b64 s[6:7], vcc
	ds_read_b32 v147, v126 offset:1536
	s_or_b64 exec, exec, s[6:7]
	v_cmp_lt_u32_e32 vcc, 7, v164
	s_and_saveexec_b64 s[6:7], vcc
	ds_read_b32 v146, v126 offset:1792
	s_or_b64 exec, exec, s[6:7]
	v_cmp_lt_u32_e32 vcc, 8, v164
	v_mov_b32_e32 v156, 0
	v_mov_b32_e32 v157, 0
	s_and_saveexec_b64 s[6:7], vcc
	ds_read_b32 v157, v126 offset:2048
	s_or_b64 exec, exec, s[6:7]
	v_cmp_lt_u32_e32 vcc, 9, v164
	s_and_saveexec_b64 s[6:7], vcc
	ds_read_b32 v156, v126 offset:2304
	s_or_b64 exec, exec, s[6:7]
	v_cmp_lt_u32_e32 vcc, 10, v164
	v_mov_b32_e32 v158, 0
	v_mov_b32_e32 v159, 0
	s_and_saveexec_b64 s[6:7], vcc
	ds_read_b32 v159, v126 offset:2560
	s_or_b64 exec, exec, s[6:7]
	v_cmp_lt_u32_e32 vcc, 11, v164
	s_and_saveexec_b64 s[6:7], vcc
	ds_read_b32 v158, v126 offset:2816
	s_or_b64 exec, exec, s[6:7]
	v_cmp_lt_u32_e32 vcc, 12, v164
	v_mov_b32_e32 v160, 0
	v_mov_b32_e32 v161, 0
	s_and_saveexec_b64 s[6:7], vcc
	ds_read_b32 v161, v126 offset:3072
	s_or_b64 exec, exec, s[6:7]
	v_cmp_lt_u32_e32 vcc, 13, v164
	s_and_saveexec_b64 s[6:7], vcc
	ds_read_b32 v160, v126 offset:3328
	s_or_b64 exec, exec, s[6:7]
	v_cmp_lt_u32_e32 vcc, 14, v164
	v_mov_b32_e32 v162, 0
	v_mov_b32_e32 v163, 0
	s_and_saveexec_b64 s[6:7], vcc
	ds_read_b32 v163, v126 offset:3584
	s_or_b64 exec, exec, s[6:7]
	v_cmp_lt_u32_e32 vcc, 15, v164
	s_and_saveexec_b64 s[6:7], vcc
	ds_read_b32 v162, v126 offset:3840
	s_or_b64 exec, exec, s[6:7]
	v_mov_b32_e32 v164, 31
	v_mov_b32_e32 v126, 0

; #define LAS __attribute__((address_space(3)))
; template <int NCH>
; __device__ __forceinline__ void dsa_topk_query(unsigned char* ws, const float* srow  , LAS unsigned* hist  , int t, int lane_in) {
;     ...
;             for (int b = 31; b >= 0; --b) { const unsigned cand = Tl | (1u << b); int cnt = 0;
; #pragma unroll
;                 for (int j = 0; j < NG; ++j) asm volatile("v_cmp_ge_u32 vcc, %1, %2\n\tv_addc_co_u32 %0, vcc, 0, %0, vcc" : "+v"(cnt) : "v"(mx[j]), "v"(cand) : "vcc");
;                 cnt = wave_sum_i(cnt);
;                 if (cnt >= 256) { Tl = cand; if (cnt <= 256 + NCH / 2 - 16) break; } }
;             LAS unsigned* cb = hist;
;             int cl = 0;
; #pragma unroll
;             for (int c = 0; c < NCH; ++c) { const bool pr = u[c] >= Tl; if (pr) cb[((cl & 31) << 6) + lane] = u[c]; cl += pr ? 1 : 0; }
.LBB0_3255:
	v_lshlrev_b32_e64 v113, v112, 1
	v_mov_b32_e32 v114, 0
	v_or_b32_e32 v113, v113, v38
	v_cmp_ge_u32 vcc, v39, v113
	v_addc_co_u32 v114, vcc, 0, v114, vcc
	s_nop 0
	v_cmp_ge_u32 vcc, v42, v113
	v_addc_co_u32 v114, vcc, 0, v114, vcc
	s_nop 0
	v_cmp_ge_u32 vcc, v43, v113
	v_addc_co_u32 v114, vcc, 0, v114, vcc
	s_nop 0
	v_cmp_ge_u32 vcc, v58, v113
	v_addc_co_u32 v114, vcc, 0, v114, vcc
	s_nop 0
	v_cmp_ge_u32 vcc, v59, v113
	v_addc_co_u32 v114, vcc, 0, v114, vcc
	s_nop 0
	v_cmp_ge_u32 vcc, v74, v113
	v_addc_co_u32 v114, vcc, 0, v114, vcc
	s_nop 0
	v_cmp_ge_u32 vcc, v75, v113
	v_addc_co_u32 v114, vcc, 0, v114, vcc
	s_nop 0
	v_cmp_ge_u32 vcc, v81, v113
	v_addc_co_u32 v114, vcc, 0, v114, vcc
	s_nop 0
	v_cmp_ge_u32 vcc, v108, v113
	v_addc_co_u32 v114, vcc, 0, v114, vcc
	s_nop 0
	v_cmp_ge_u32 vcc, v109, v113
	v_addc_co_u32 v114, vcc, 0, v114, vcc
	s_nop 0
	v_cmp_ge_u32 vcc, v110, v113
	v_addc_co_u32 v114, vcc, 0, v114, vcc
	s_nop 0
	v_cmp_ge_u32 vcc, v111, v113
	v_addc_co_u32 v114, vcc, 0, v114, vcc
	s_nop 1
	v_add_u32_dpp v114, v114, v114 quad_perm:[1,0,3,2] row_mask:0xf bank_mask:0xf bound_ctrl:1
	s_nop 1
	v_add_u32_dpp v114, v114, v114 quad_perm:[2,3,0,1] row_mask:0xf bank_mask:0xf bound_ctrl:1
	s_nop 1
	v_add_u32_dpp v114, v114, v114 row_half_mirror row_mask:0xf bank_mask:0xf bound_ctrl:1
	s_nop 1
	v_add_u32_dpp v114, v114, v114 row_mirror row_mask:0xf bank_mask:0xf bound_ctrl:1
	s_nop 0
	v_readlane_b32 s0, v114, 0
	v_readlane_b32 s1, v114, 16
	s_add_i32 s0, s1, s0
	v_readlane_b32 s1, v114, 32
	s_add_i32 s0, s0, s1
	v_readlane_b32 s1, v114, 48
	s_add_i32 s0, s0, s1
	s_cmpk_lt_i32 s0, 0x100
	s_cselect_b64 vcc, -1, 0
	s_addk_i32 s0, 0xff00
	s_cmp_lt_u32 s0, 33
	v_cndmask_b32_e32 v38, v113, v38, vcc
	s_cselect_b64 s[0:1], -1, 0
	v_subrev_co_u32_e32 v112, vcc, 1, v112
	s_or_b64 s[0:1], s[0:1], vcc
	s_andn2_b64 vcc, exec, s[0:1]
	s_cbranch_vccnz .LBB0_3255
	v_lshl_add_u32 v39, v80, 2, s5
	v_cmp_ge_u32_e32 vcc, v106, v38
	v_mov_b32_e32 v42, 0
	s_and_saveexec_b64 s[0:1], vcc
	v_mov_b32_e32 v42, 64
	ds_write_b32 v39, v106
	s_or_b64 exec, exec, s[0:1]
	v_cmp_ge_u32_e64 s[0:1], v107, v38
	s_and_saveexec_b64 s[6:7], s[0:1]
	v_lshl_add_u32 v42, v42, 2, v39
	ds_write_b32 v42, v107
	s_or_b64 exec, exec, s[6:7]
	v_cndmask_b32_e64 v42, 0, 1, vcc
	v_cndmask_b32_e64 v43, 0, 1, s[0:1]
	v_add_u32_e32 v42, v42, v43
	v_cmp_ge_u32_e32 vcc, v104, v38
	s_and_saveexec_b64 s[0:1], vcc
	v_lshl_add_u32 v43, v42, 8, v39
	ds_write_b32 v43, v104
	s_or_b64 exec, exec, s[0:1]
	v_cndmask_b32_e64 v43, 0, 1, vcc
	v_add_u32_e32 v42, v42, v43
	v_cmp_ge_u32_e32 vcc, v105, v38
	s_and_saveexec_b64 s[0:1], vcc
	v_lshl_add_u32 v43, v42, 8, v39
	ds_write_b32 v43, v105
	s_or_b64 exec, exec, s[0:1]
	v_cndmask_b32_e64 v43, 0, 1, vcc
	v_add_u32_e32 v42, v42, v43
	v_cmp_ge_u32_e32 vcc, v102, v38
	s_and_saveexec_b64 s[0:1], vcc
	v_lshl_add_u32 v43, v42, 8, v39
	ds_write_b32 v43, v102
	s_or_b64 exec, exec, s[0:1]
	v_cndmask_b32_e64 v43, 0, 1, vcc
	v_add_u32_e32 v42, v42, v43
	v_cmp_ge_u32_e32 vcc, v101, v38
	s_and_saveexec_b64 s[0:1], vcc
	v_lshl_add_u32 v43, v42, 8, v39
	ds_write_b32 v43, v101
	s_or_b64 exec, exec, s[0:1]
	v_cndmask_b32_e64 v43, 0, 1, vcc
	v_add_u32_e32 v42, v42, v43
	v_cmp_ge_u32_e32 vcc, v100, v38
	v_min_u32_e32 v43, 31, v42
	v_lshl_add_u32 v43, v43, 8, v39
	ds_write_b32 v43, v100
	v_addc_co_u32_e32 v42, vcc, 0, v42, vcc
	v_cmp_ge_u32_e32 vcc, v103, v38
	v_min_u32_e32 v43, 31, v42
	v_lshl_add_u32 v43, v43, 8, v39
	ds_write_b32 v43, v103
	v_addc_co_u32_e32 v42, vcc, 0, v42, vcc
	v_cmp_ge_u32_e32 vcc, v98, v38
	v_min_u32_e32 v43, 31, v42
	v_lshl_add_u32 v43, v43, 8, v39
	ds_write_b32 v43, v98
	v_addc_co_u32_e32 v42, vcc, 0, v42, vcc
	v_cmp_ge_u32_e32 vcc, v99, v38
	v_min_u32_e32 v43, 31, v42
	v_lshl_add_u32 v43, v43, 8, v39
	ds_write_b32 v43, v99
	v_addc_co_u32_e32 v42, vcc, 0, v42, vcc
	v_cmp_ge_u32_e32 vcc, v96, v38
	v_min_u32_e32 v43, 31, v42
	v_lshl_add_u32 v43, v43, 8, v39
	ds_write_b32 v43, v96
	v_addc_co_u32_e32 v42, vcc, 0, v42, vcc
	v_cmp_ge_u32_e32 vcc, v97, v38
	v_min_u32_e32 v43, 31, v42
	v_lshl_add_u32 v43, v43, 8, v39
	ds_write_b32 v43, v97
	v_addc_co_u32_e32 v42, vcc, 0, v42, vcc
	v_cmp_ge_u32_e32 vcc, v94, v38
	v_min_u32_e32 v43, 31, v42
	v_lshl_add_u32 v43, v43, 8, v39
	ds_write_b32 v43, v94
	v_addc_co_u32_e32 v42, vcc, 0, v42, vcc
	v_cmp_ge_u32_e32 vcc, v95, v38
	v_min_u32_e32 v43, 31, v42
	v_lshl_add_u32 v43, v43, 8, v39
	ds_write_b32 v43, v95
	v_addc_co_u32_e32 v42, vcc, 0, v42, vcc
	v_cmp_ge_u32_e32 vcc, v92, v38
	v_min_u32_e32 v43, 31, v42
	v_lshl_add_u32 v43, v43, 8, v39
	ds_write_b32 v43, v92
	v_addc_co_u32_e32 v42, vcc, 0, v42, vcc
	v_cmp_ge_u32_e32 vcc, v93, v38
	v_min_u32_e32 v43, 31, v42
	v_lshl_add_u32 v43, v43, 8, v39
	ds_write_b32 v43, v93
	v_addc_co_u32_e32 v42, vcc, 0, v42, vcc
	v_cmp_ge_u32_e32 vcc, v90, v38
	v_min_u32_e32 v43, 31, v42
	v_lshl_add_u32 v43, v43, 8, v39
	ds_write_b32 v43, v90
	v_addc_co_u32_e32 v42, vcc, 0, v42, vcc
	v_cmp_ge_u32_e32 vcc, v91, v38
	v_min_u32_e32 v43, 31, v42
	v_lshl_add_u32 v43, v43, 8, v39
	ds_write_b32 v43, v91
	v_addc_co_u32_e32 v42, vcc, 0, v42, vcc
	v_cmp_ge_u32_e32 vcc, v88, v38
	v_min_u32_e32 v43, 31, v42
	v_lshl_add_u32 v43, v43, 8, v39
	ds_write_b32 v43, v88
	v_addc_co_u32_e32 v42, vcc, 0, v42, vcc
	v_cmp_ge_u32_e32 vcc, v89, v38
	v_min_u32_e32 v43, 31, v42
	v_lshl_add_u32 v43, v43, 8, v39
	ds_write_b32 v43, v89
	v_addc_co_u32_e32 v42, vcc, 0, v42, vcc
	v_cmp_ge_u32_e32 vcc, v86, v38
	v_min_u32_e32 v43, 31, v42
	v_lshl_add_u32 v43, v43, 8, v39
	ds_write_b32 v43, v86
	v_addc_co_u32_e32 v42, vcc, 0, v42, vcc
	v_cmp_ge_u32_e32 vcc, v87, v38
	v_min_u32_e32 v43, 31, v42
	v_lshl_add_u32 v43, v43, 8, v39
; template <int NCH>
; __device__ __forceinline__ void dsa_topk_query(unsigned char* ws, const float* srow  , LAS unsigned* hist  , int t, int lane_in) {
;     ...
;             for (int c = 0; c < NCH; ++c) { const bool pr = u[c] >= Tl; if (pr) cb[((cl & 31) << 6) + lane] = u[c]; cl += pr ? 1 : 0; }
	ds_write_b32 v43, v87
	v_addc_co_u32_e32 v42, vcc, 0, v42, vcc
	v_cmp_ge_u32_e32 vcc, v84, v38
	v_min_u32_e32 v43, 31, v42
	v_lshl_add_u32 v43, v43, 8, v39
	ds_write_b32 v43, v84
	v_addc_co_u32_e32 v42, vcc, 0, v42, vcc
	v_cmp_ge_u32_e32 vcc, v85, v38
	v_min_u32_e32 v43, 31, v42
	v_lshl_add_u32 v43, v43, 8, v39
	ds_write_b32 v43, v85
	v_addc_co_u32_e32 v42, vcc, 0, v42, vcc
	v_cmp_ge_u32_e32 vcc, v82, v38
	v_min_u32_e32 v43, 31, v42
	v_lshl_add_u32 v43, v43, 8, v39
	ds_write_b32 v43, v82
	v_addc_co_u32_e32 v42, vcc, 0, v42, vcc
	v_cmp_ge_u32_e32 vcc, v83, v38
	v_min_u32_e32 v43, 31, v42
	v_lshl_add_u32 v43, v43, 8, v39
	ds_write_b32 v43, v83
	v_addc_co_u32_e32 v42, vcc, 0, v42, vcc
	v_cmp_ge_u32_e32 vcc, v78, v38
	v_min_u32_e32 v43, 31, v42
	v_lshl_add_u32 v43, v43, 8, v39
	ds_write_b32 v43, v78
	v_addc_co_u32_e32 v42, vcc, 0, v42, vcc
	v_cmp_ge_u32_e32 vcc, v79, v38
	v_min_u32_e32 v43, 31, v42
	v_lshl_add_u32 v43, v43, 8, v39
	ds_write_b32 v43, v79
	v_addc_co_u32_e32 v42, vcc, 0, v42, vcc
	v_cmp_ge_u32_e32 vcc, v76, v38
	v_min_u32_e32 v43, 31, v42
	v_lshl_add_u32 v43, v43, 8, v39
	ds_write_b32 v43, v76
	v_addc_co_u32_e32 v42, vcc, 0, v42, vcc
	v_cmp_ge_u32_e32 vcc, v77, v38
	v_min_u32_e32 v43, 31, v42
	v_lshl_add_u32 v43, v43, 8, v39
	ds_write_b32 v43, v77
	v_addc_co_u32_e32 v42, vcc, 0, v42, vcc
	v_cmp_ge_u32_e32 vcc, v72, v38
	v_min_u32_e32 v43, 31, v42
	v_lshl_add_u32 v43, v43, 8, v39
	ds_write_b32 v43, v72
	v_addc_co_u32_e32 v42, vcc, 0, v42, vcc
	v_cmp_ge_u32_e32 vcc, v73, v38
	v_min_u32_e32 v43, 31, v42
	v_lshl_add_u32 v43, v43, 8, v39
	ds_write_b32 v43, v73
	v_addc_co_u32_e32 v42, vcc, 0, v42, vcc
	v_cmp_ge_u32_e32 vcc, v70, v38
	v_min_u32_e32 v43, 31, v42
	v_lshl_add_u32 v43, v43, 8, v39
	ds_write_b32 v43, v70
	v_addc_co_u32_e32 v42, vcc, 0, v42, vcc
	v_cmp_ge_u32_e32 vcc, v71, v38
	v_min_u32_e32 v43, 31, v42
	v_lshl_add_u32 v43, v43, 8, v39
	ds_write_b32 v43, v71
	v_addc_co_u32_e32 v42, vcc, 0, v42, vcc
	v_cmp_ge_u32_e32 vcc, v68, v38
	v_min_u32_e32 v43, 31, v42
	v_lshl_add_u32 v43, v43, 8, v39
	ds_write_b32 v43, v68
	v_addc_co_u32_e32 v42, vcc, 0, v42, vcc
	v_cmp_ge_u32_e32 vcc, v69, v38
	v_min_u32_e32 v43, 31, v42
	v_lshl_add_u32 v43, v43, 8, v39
	ds_write_b32 v43, v69
	v_addc_co_u32_e32 v42, vcc, 0, v42, vcc
	v_cmp_ge_u32_e32 vcc, v66, v38
	v_min_u32_e32 v43, 31, v42
	v_lshl_add_u32 v43, v43, 8, v39
	ds_write_b32 v43, v66
	v_addc_co_u32_e32 v42, vcc, 0, v42, vcc
	v_cmp_ge_u32_e32 vcc, v67, v38
	v_min_u32_e32 v43, 31, v42
	v_lshl_add_u32 v43, v43, 8, v39
	ds_write_b32 v43, v67
	v_addc_co_u32_e32 v42, vcc, 0, v42, vcc
	v_cmp_ge_u32_e32 vcc, v64, v38
	v_min_u32_e32 v43, 31, v42
	v_lshl_add_u32 v43, v43, 8, v39
	ds_write_b32 v43, v64
	v_addc_co_u32_e32 v42, vcc, 0, v42, vcc
	v_cmp_ge_u32_e32 vcc, v65, v38
	v_min_u32_e32 v43, 31, v42
	v_lshl_add_u32 v43, v43, 8, v39
	ds_write_b32 v43, v65
	v_addc_co_u32_e32 v42, vcc, 0, v42, vcc
	v_cmp_ge_u32_e32 vcc, v62, v38
	v_min_u32_e32 v43, 31, v42
	v_lshl_add_u32 v43, v43, 8, v39
	ds_write_b32 v43, v62
	v_addc_co_u32_e32 v42, vcc, 0, v42, vcc
	v_cmp_ge_u32_e32 vcc, v63, v38
	v_min_u32_e32 v43, 31, v42
	v_lshl_add_u32 v43, v43, 8, v39
	ds_write_b32 v43, v63
	v_addc_co_u32_e32 v42, vcc, 0, v42, vcc
	v_cmp_ge_u32_e32 vcc, v60, v38
	v_min_u32_e32 v43, 31, v42
	v_lshl_add_u32 v43, v43, 8, v39
	ds_write_b32 v43, v60
	v_addc_co_u32_e32 v42, vcc, 0, v42, vcc
	v_cmp_ge_u32_e32 vcc, v61, v38
	v_min_u32_e32 v43, 31, v42
	v_lshl_add_u32 v43, v43, 8, v39
	ds_write_b32 v43, v61
	v_addc_co_u32_e32 v42, vcc, 0, v42, vcc
	v_cmp_ge_u32_e32 vcc, v56, v38
	v_min_u32_e32 v43, 31, v42
	v_lshl_add_u32 v43, v43, 8, v39
	ds_write_b32 v43, v56
	v_addc_co_u32_e32 v42, vcc, 0, v42, vcc
	v_cmp_ge_u32_e32 vcc, v57, v38
	v_min_u32_e32 v43, 31, v42
	v_lshl_add_u32 v43, v43, 8, v39
	ds_write_b32 v43, v57
	v_addc_co_u32_e32 v42, vcc, 0, v42, vcc
	v_cmp_ge_u32_e32 vcc, v54, v38
	v_min_u32_e32 v43, 31, v42
	v_lshl_add_u32 v43, v43, 8, v39
	ds_write_b32 v43, v54
	v_addc_co_u32_e32 v42, vcc, 0, v42, vcc
	v_cmp_ge_u32_e32 vcc, v55, v38
	v_min_u32_e32 v43, 31, v42
	v_lshl_add_u32 v43, v43, 8, v39
	ds_write_b32 v43, v55
	v_addc_co_u32_e32 v42, vcc, 0, v42, vcc
	v_cmp_ge_u32_e32 vcc, v52, v38
	v_min_u32_e32 v43, 31, v42
	v_lshl_add_u32 v43, v43, 8, v39
	ds_write_b32 v43, v52
	v_addc_co_u32_e32 v42, vcc, 0, v42, vcc
	v_cmp_ge_u32_e32 vcc, v53, v38
	v_min_u32_e32 v43, 31, v42
	v_lshl_add_u32 v43, v43, 8, v39
	ds_write_b32 v43, v53
	v_addc_co_u32_e32 v42, vcc, 0, v42, vcc
	v_cmp_ge_u32_e32 vcc, v50, v38
	v_min_u32_e32 v43, 31, v42
	v_lshl_add_u32 v43, v43, 8, v39
	ds_write_b32 v43, v50
	v_addc_co_u32_e32 v42, vcc, 0, v42, vcc
	v_cmp_ge_u32_e32 vcc, v51, v38
	v_min_u32_e32 v43, 31, v42
	v_lshl_add_u32 v43, v43, 8, v39
	ds_write_b32 v43, v51
	v_addc_co_u32_e32 v42, vcc, 0, v42, vcc
	v_cmp_ge_u32_e32 vcc, v48, v38
	v_min_u32_e32 v43, 31, v42
	v_lshl_add_u32 v43, v43, 8, v39
	ds_write_b32 v43, v48
	v_addc_co_u32_e32 v42, vcc, 0, v42, vcc
	v_cmp_ge_u32_e32 vcc, v49, v38
	v_min_u32_e32 v43, 31, v42
	v_lshl_add_u32 v43, v43, 8, v39
	ds_write_b32 v43, v49
	v_addc_co_u32_e32 v42, vcc, 0, v42, vcc
	v_cmp_ge_u32_e32 vcc, v46, v38
	v_min_u32_e32 v43, 31, v42
	v_lshl_add_u32 v43, v43, 8, v39
	ds_write_b32 v43, v46
	v_addc_co_u32_e32 v42, vcc, 0, v42, vcc
	v_cmp_ge_u32_e32 vcc, v47, v38
	v_min_u32_e32 v43, 31, v42
	v_lshl_add_u32 v43, v43, 8, v39
	ds_write_b32 v43, v47
	v_addc_co_u32_e32 v42, vcc, 0, v42, vcc
	v_cmp_ge_u32_e32 vcc, v44, v38
	v_min_u32_e32 v43, 31, v42
	v_lshl_add_u32 v43, v43, 8, v39
	ds_write_b32 v43, v44
	v_addc_co_u32_e32 v42, vcc, 0, v42, vcc
	v_cmp_ge_u32_e32 vcc, v45, v38
	v_min_u32_e32 v43, 31, v42
	v_lshl_add_u32 v43, v43, 8, v39
; template <int NCH>
; __device__ __forceinline__ void dsa_topk_query(unsigned char* ws, const float* srow  , LAS unsigned* hist  , int t, int lane_in) {
;     ...
;             for (int c = 0; c < NCH; ++c) { const bool pr = u[c] >= Tl; if (pr) cb[((cl & 31) << 6) + lane] = u[c]; cl += pr ? 1 : 0; }
;             if (wave_max_i(cl) <= 16) {
;                 unsigned k[16];
; #pragma unroll
;                 for (int i = 0; i < 16; ++i) { k[i] = 0u; if (i < cl) k[i] = cb[(i << 6) + lane]; }
	ds_write_b32 v43, v45
	v_addc_co_u32_e32 v42, vcc, 0, v42, vcc
	v_cmp_ge_u32_e32 vcc, v40, v38
	v_min_u32_e32 v43, 31, v42
	v_lshl_add_u32 v43, v43, 8, v39
	ds_write_b32 v43, v40
	v_addc_co_u32_e32 v42, vcc, 0, v42, vcc
	v_cmp_ge_u32_e32 vcc, v41, v38
	v_min_u32_e32 v43, 31, v42
	v_lshl_add_u32 v43, v43, 8, v39
	ds_write_b32 v43, v41
	v_addc_co_u32_e32 v42, vcc, 0, v42, vcc
	v_cmp_ge_u32_e32 vcc, v36, v38
	v_min_u32_e32 v43, 31, v42
	v_lshl_add_u32 v43, v43, 8, v39
	ds_write_b32 v43, v36
	v_addc_co_u32_e32 v42, vcc, 0, v42, vcc
	v_cmp_ge_u32_e32 vcc, v37, v38
	v_min_u32_e32 v43, 31, v42
	v_lshl_add_u32 v43, v43, 8, v39
	ds_write_b32 v43, v37
	v_addc_co_u32_e32 v42, vcc, 0, v42, vcc
	v_cmp_ge_u32_e32 vcc, v2, v38
	v_min_u32_e32 v43, 31, v42
	v_lshl_add_u32 v43, v43, 8, v39
	ds_write_b32 v43, v2
	v_addc_co_u32_e32 v42, vcc, 0, v42, vcc
	v_cmp_ge_u32_e32 vcc, v1, v38
	v_min_u32_e32 v43, 31, v42
	v_lshl_add_u32 v43, v43, 8, v39
	ds_write_b32 v43, v1
	v_addc_co_u32_e32 v42, vcc, 0, v42, vcc
	v_cmp_ge_u32_e32 vcc, v32, v38
	v_min_u32_e32 v43, 31, v42
	v_lshl_add_u32 v43, v43, 8, v39
	ds_write_b32 v43, v32
	v_addc_co_u32_e32 v42, vcc, 0, v42, vcc
	v_cmp_ge_u32_e32 vcc, v33, v38
	v_min_u32_e32 v43, 31, v42
	v_lshl_add_u32 v43, v43, 8, v39
	ds_write_b32 v43, v33
	v_addc_co_u32_e32 v42, vcc, 0, v42, vcc
	v_cmp_ge_u32_e32 vcc, v34, v38
	v_min_u32_e32 v43, 31, v42
	v_lshl_add_u32 v43, v43, 8, v39
	ds_write_b32 v43, v34
	v_addc_co_u32_e32 v42, vcc, 0, v42, vcc
	v_cmp_ge_u32_e32 vcc, v35, v38
	v_min_u32_e32 v43, 31, v42
	v_lshl_add_u32 v43, v43, 8, v39
	ds_write_b32 v43, v35
	v_addc_co_u32_e32 v42, vcc, 0, v42, vcc
	v_cmp_ge_u32_e32 vcc, v28, v38
	v_min_u32_e32 v43, 31, v42
	v_lshl_add_u32 v43, v43, 8, v39
	ds_write_b32 v43, v28
	v_addc_co_u32_e32 v42, vcc, 0, v42, vcc
	v_cmp_ge_u32_e32 vcc, v29, v38
	v_min_u32_e32 v43, 31, v42
	v_lshl_add_u32 v43, v43, 8, v39
	ds_write_b32 v43, v29
	v_addc_co_u32_e32 v42, vcc, 0, v42, vcc
	v_cmp_ge_u32_e32 vcc, v30, v38
	v_min_u32_e32 v43, 31, v42
	v_lshl_add_u32 v43, v43, 8, v39
	ds_write_b32 v43, v30
	v_addc_co_u32_e32 v42, vcc, 0, v42, vcc
	v_cmp_ge_u32_e32 vcc, v31, v38
	v_min_u32_e32 v43, 31, v42
	v_lshl_add_u32 v43, v43, 8, v39
	ds_write_b32 v43, v31
	v_addc_co_u32_e32 v42, vcc, 0, v42, vcc
	v_cmp_ge_u32_e32 vcc, v24, v38
	v_min_u32_e32 v43, 31, v42
	v_lshl_add_u32 v43, v43, 8, v39
	ds_write_b32 v43, v24
	v_addc_co_u32_e32 v42, vcc, 0, v42, vcc
	v_cmp_ge_u32_e32 vcc, v25, v38
	v_min_u32_e32 v43, 31, v42
	v_lshl_add_u32 v43, v43, 8, v39
	ds_write_b32 v43, v25
	v_addc_co_u32_e32 v42, vcc, 0, v42, vcc
	v_cmp_ge_u32_e32 vcc, v26, v38
	v_min_u32_e32 v43, 31, v42
	v_lshl_add_u32 v43, v43, 8, v39
	ds_write_b32 v43, v26
	v_addc_co_u32_e32 v42, vcc, 0, v42, vcc
	v_cmp_ge_u32_e32 vcc, v27, v38
	v_min_u32_e32 v43, 31, v42
	v_lshl_add_u32 v43, v43, 8, v39
	ds_write_b32 v43, v27
	v_addc_co_u32_e32 v42, vcc, 0, v42, vcc
	v_cmp_ge_u32_e32 vcc, v20, v38
	v_min_u32_e32 v43, 31, v42
	v_lshl_add_u32 v43, v43, 8, v39
	ds_write_b32 v43, v20
	v_addc_co_u32_e32 v42, vcc, 0, v42, vcc
	v_cmp_ge_u32_e32 vcc, v21, v38
	v_min_u32_e32 v43, 31, v42
	v_lshl_add_u32 v43, v43, 8, v39
	ds_write_b32 v43, v21
	v_addc_co_u32_e32 v42, vcc, 0, v42, vcc
	v_cmp_ge_u32_e32 vcc, v22, v38
	v_min_u32_e32 v43, 31, v42
	v_lshl_add_u32 v43, v43, 8, v39
	ds_write_b32 v43, v22
	v_addc_co_u32_e32 v42, vcc, 0, v42, vcc
	v_cmp_ge_u32_e32 vcc, v23, v38
	v_min_u32_e32 v43, 31, v42
	v_lshl_add_u32 v43, v43, 8, v39
	ds_write_b32 v43, v23
	v_addc_co_u32_e32 v42, vcc, 0, v42, vcc
	v_cmp_ge_u32_e32 vcc, v16, v38
	v_min_u32_e32 v43, 31, v42
	v_lshl_add_u32 v43, v43, 8, v39
	ds_write_b32 v43, v16
	v_addc_co_u32_e32 v42, vcc, 0, v42, vcc
	v_cmp_ge_u32_e32 vcc, v17, v38
	v_min_u32_e32 v43, 31, v42
	v_lshl_add_u32 v43, v43, 8, v39
	ds_write_b32 v43, v17
	v_addc_co_u32_e32 v42, vcc, 0, v42, vcc
	v_cmp_ge_u32_e32 vcc, v18, v38
	v_min_u32_e32 v43, 31, v42
	v_lshl_add_u32 v43, v43, 8, v39
	ds_write_b32 v43, v18
	v_addc_co_u32_e32 v42, vcc, 0, v42, vcc
	v_cmp_ge_u32_e32 vcc, v19, v38
	v_min_u32_e32 v43, 31, v42
	v_lshl_add_u32 v43, v43, 8, v39
	ds_write_b32 v43, v19
	v_addc_co_u32_e32 v42, vcc, 0, v42, vcc
	v_cmp_ge_u32_e32 vcc, v12, v38
	v_min_u32_e32 v43, 31, v42
	v_lshl_add_u32 v43, v43, 8, v39
	ds_write_b32 v43, v12
	v_addc_co_u32_e32 v42, vcc, 0, v42, vcc
	v_cmp_ge_u32_e32 vcc, v13, v38
	v_min_u32_e32 v43, 31, v42
	v_lshl_add_u32 v43, v43, 8, v39
	ds_write_b32 v43, v13
	v_addc_co_u32_e32 v42, vcc, 0, v42, vcc
	v_cmp_ge_u32_e32 vcc, v14, v38
	v_min_u32_e32 v43, 31, v42
	v_lshl_add_u32 v43, v43, 8, v39
	ds_write_b32 v43, v14
	v_addc_co_u32_e32 v42, vcc, 0, v42, vcc
	v_cmp_ge_u32_e32 vcc, v15, v38
	v_min_u32_e32 v43, 31, v42
	v_lshl_add_u32 v43, v43, 8, v39
	ds_write_b32 v43, v15
	v_addc_co_u32_e32 v42, vcc, 0, v42, vcc
	v_cmp_ge_u32_e32 vcc, v8, v38
	v_min_u32_e32 v43, 31, v42
	v_lshl_add_u32 v43, v43, 8, v39
	ds_write_b32 v43, v8
	v_addc_co_u32_e32 v42, vcc, 0, v42, vcc
	v_cmp_ge_u32_e32 vcc, v9, v38
	v_min_u32_e32 v43, 31, v42
	v_lshl_add_u32 v43, v43, 8, v39
	ds_write_b32 v43, v9
	v_addc_co_u32_e32 v42, vcc, 0, v42, vcc
	v_cmp_ge_u32_e32 vcc, v10, v38
	v_min_u32_e32 v43, 31, v42
	v_lshl_add_u32 v43, v43, 8, v39
	ds_write_b32 v43, v10
	v_addc_co_u32_e32 v42, vcc, 0, v42, vcc
	v_cmp_ge_u32_e32 vcc, v11, v38
	v_min_u32_e32 v43, 31, v42
	v_lshl_add_u32 v43, v43, 8, v39
	ds_write_b32 v43, v11
	v_addc_co_u32_e32 v42, vcc, 0, v42, vcc
	v_cmp_ge_u32_e32 vcc, v4, v38
	v_min_u32_e32 v43, 31, v42
	v_lshl_add_u32 v43, v43, 8, v39
	ds_write_b32 v43, v4
	v_addc_co_u32_e32 v42, vcc, 0, v42, vcc
	v_cmp_ge_u32_e32 vcc, v5, v38
	v_min_u32_e32 v43, 31, v42
	v_lshl_add_u32 v43, v43, 8, v39
	ds_write_b32 v43, v5
	v_addc_co_u32_e32 v42, vcc, 0, v42, vcc
	v_cmp_ge_u32_e32 vcc, v6, v38
	v_min_u32_e32 v43, 31, v42
	v_lshl_add_u32 v43, v43, 8, v39
	ds_write_b32 v43, v6
	v_addc_co_u32_e32 v42, vcc, 0, v42, vcc
	v_cmp_ge_u32_e32 vcc, v7, v38
	s_and_saveexec_b64 s[0:1], vcc
	v_lshlrev_b32_e32 v43, 8, v42
	v_and_b32_e32 v43, 0x1f00, v43
	v_add_u32_e32 v43, v39, v43
	ds_write_b32 v43, v7
	s_or_b64 exec, exec, s[0:1]
	v_cndmask_b32_e64 v43, 0, 1, vcc
	v_add_u32_e32 v74, v42, v43
	s_mov_b32 s10, 0
	s_nop 0
	v_max_i32_dpp v42, v74, v74 quad_perm:[1,0,3,2] row_mask:0xf bank_mask:0xf bound_ctrl:1
	s_nop 1
	v_max_i32_dpp v42, v42, v42 quad_perm:[2,3,0,1] row_mask:0xf bank_mask:0xf bound_ctrl:1
	s_nop 1
	v_max_i32_dpp v42, v42, v42 row_half_mirror row_mask:0xf bank_mask:0xf bound_ctrl:1
	s_nop 1
	v_max_i32_dpp v42, v42, v42 row_mirror row_mask:0xf bank_mask:0xf bound_ctrl:1
	s_nop 0
	v_readlane_b32 s2, v42, 32
	v_readlane_b32 s6, v42, 48
	v_readlane_b32 s1, v42, 16
	s_max_i32 s2, s2, s6
	v_readlane_b32 s0, v42, 0
	v_mov_b32_e32 v42, s1
	v_mov_b32_e32 v43, s2
	v_max3_i32 v42, s0, v42, v43
	v_cmp_lt_i32_e64 s[0:1], 16, v42
	s_and_b64 vcc, exec, s[0:1]
	s_cbranch_vccnz .LBB0_3485
; template <int NCH>
; __device__ __forceinline__ void dsa_topk_query(unsigned char* ws, const float* srow  , LAS unsigned* hist  , int t, int lane_in) {
;     ...
;                 unsigned k[16];
; #pragma unroll
;                 for (int i = 0; i < 16; ++i) { k[i] = 0u; if (i < cl) k[i] = cb[(i << 6) + lane]; }
	v_mov_b32_e32 v42, 0
	v_cmp_ne_u32_e32 vcc, 0, v74
	v_mov_b32_e32 v43, 0
	s_and_saveexec_b64 s[6:7], vcc
	ds_read_b32 v43, v39
	s_or_b64 exec, exec, s[6:7]
	v_cmp_lt_u32_e32 vcc, 1, v74
	s_and_saveexec_b64 s[6:7], vcc
	ds_read_b32 v42, v39 offset:256
	s_or_b64 exec, exec, s[6:7]
	v_cmp_lt_u32_e32 vcc, 2, v74
	v_mov_b32_e32 v58, 0
	v_mov_b32_e32 v59, 0
	s_and_saveexec_b64 s[6:7], vcc
	ds_read_b32 v59, v39 offset:512
	s_or_b64 exec, exec, s[6:7]
	v_cmp_lt_u32_e32 vcc, 3, v74
	s_and_saveexec_b64 s[6:7], vcc
	ds_read_b32 v58, v39 offset:768
	s_or_b64 exec, exec, s[6:7]
	v_cmp_lt_u32_e32 vcc, 4, v74
	v_mov_b32_e32 v75, 0
	v_mov_b32_e32 v81, 0
	s_and_saveexec_b64 s[6:7], vcc
	ds_read_b32 v81, v39 offset:1024
	s_or_b64 exec, exec, s[6:7]
	v_cmp_lt_u32_e32 vcc, 5, v74
	s_and_saveexec_b64 s[6:7], vcc
	ds_read_b32 v75, v39 offset:1280
	s_or_b64 exec, exec, s[6:7]
	v_cmp_lt_u32_e32 vcc, 6, v74
	v_mov_b32_e32 v108, 0
	v_mov_b32_e32 v109, 0
	s_and_saveexec_b64 s[6:7], vcc
	ds_read_b32 v109, v39 offset:1536
	s_or_b64 exec, exec, s[6:7]
	v_cmp_lt_u32_e32 vcc, 7, v74
	s_and_saveexec_b64 s[6:7], vcc
	ds_read_b32 v108, v39 offset:1792
	s_or_b64 exec, exec, s[6:7]
	v_cmp_lt_u32_e32 vcc, 8, v74
	v_mov_b32_e32 v110, 0
	v_mov_b32_e32 v111, 0
	s_and_saveexec_b64 s[6:7], vcc
	ds_read_b32 v111, v39 offset:2048
	s_or_b64 exec, exec, s[6:7]
	v_cmp_lt_u32_e32 vcc, 9, v74
	s_and_saveexec_b64 s[6:7], vcc
	ds_read_b32 v110, v39 offset:2304
	s_or_b64 exec, exec, s[6:7]
	v_cmp_lt_u32_e32 vcc, 10, v74
	v_mov_b32_e32 v112, 0
	v_mov_b32_e32 v113, 0
	s_and_saveexec_b64 s[6:7], vcc
	ds_read_b32 v113, v39 offset:2560
	s_or_b64 exec, exec, s[6:7]
	v_cmp_lt_u32_e32 vcc, 11, v74
	s_and_saveexec_b64 s[6:7], vcc
	ds_read_b32 v112, v39 offset:2816
	s_or_b64 exec, exec, s[6:7]
	v_cmp_lt_u32_e32 vcc, 12, v74
	v_mov_b32_e32 v114, 0
	v_mov_b32_e32 v115, 0
	s_and_saveexec_b64 s[6:7], vcc
	ds_read_b32 v115, v39 offset:3072
	s_or_b64 exec, exec, s[6:7]
	v_cmp_lt_u32_e32 vcc, 13, v74
	s_and_saveexec_b64 s[6:7], vcc
	ds_read_b32 v114, v39 offset:3328
	s_or_b64 exec, exec, s[6:7]
	v_cmp_lt_u32_e32 vcc, 14, v74
	v_mov_b32_e32 v116, 0
	v_mov_b32_e32 v117, 0
	s_and_saveexec_b64 s[6:7], vcc
	ds_read_b32 v117, v39 offset:3584
	s_or_b64 exec, exec, s[6:7]
	v_cmp_lt_u32_e32 vcc, 15, v74
	s_and_saveexec_b64 s[6:7], vcc
	ds_read_b32 v116, v39 offset:3840
	s_or_b64 exec, exec, s[6:7]
	v_mov_b32_e32 v39, 31
	v_mov_b32_e32 v74, 0

; #define LAS __attribute__((address_space(3)))
; template <int NCH>
; __device__ __forceinline__ void dsa_topk_query(unsigned char* ws, const float* srow  , LAS unsigned* hist  , int t, int lane_in) {
;     ...
;             for (int b = 31; b >= 0; --b) { const unsigned cand = Tl | (1u << b); int cnt = 0;
; #pragma unroll
;                 for (int j = 0; j < NG; ++j) asm volatile("v_cmp_ge_u32 vcc, %1, %2\n\tv_addc_co_u32 %0, vcc, 0, %0, vcc" : "+v"(cnt) : "v"(mx[j]), "v"(cand) : "vcc");
;                 cnt = wave_sum_i(cnt);
;                 if (cnt >= 256) { Tl = cand; if (cnt <= 256 + NCH / 2 - 16) break; } }
;             LAS unsigned* cb = hist;
;             int cl = 0;
; #pragma unroll
;             for (int c = 0; c < NCH; ++c) { const bool pr = u[c] >= Tl; if (pr) cb[((cl & 31) << 6) + lane] = u[c]; cl += pr ? 1 : 0; }
.LBB0_3987:
	v_lshlrev_b32_e64 v77, v76, 1
	v_mov_b32_e32 v78, 0
	v_or_b32_e32 v77, v77, v61
	v_cmp_ge_u32 vcc, v68, v77
	v_addc_co_u32 v78, vcc, 0, v78, vcc
	s_nop 0
	v_cmp_ge_u32 vcc, v69, v77
	v_addc_co_u32 v78, vcc, 0, v78, vcc
	s_nop 0
	v_cmp_ge_u32 vcc, v70, v77
	v_addc_co_u32 v78, vcc, 0, v78, vcc
	s_nop 0
	v_cmp_ge_u32 vcc, v71, v77
	v_addc_co_u32 v78, vcc, 0, v78, vcc
	s_nop 0
	v_cmp_ge_u32 vcc, v72, v77
	v_addc_co_u32 v78, vcc, 0, v78, vcc
	s_nop 0
	v_cmp_ge_u32 vcc, v73, v77
	v_addc_co_u32 v78, vcc, 0, v78, vcc
	s_nop 0
	v_cmp_ge_u32 vcc, v74, v77
	v_addc_co_u32 v78, vcc, 0, v78, vcc
	s_nop 0
	v_cmp_ge_u32 vcc, v75, v77
	v_addc_co_u32 v78, vcc, 0, v78, vcc
	s_nop 1
	v_add_u32_dpp v78, v78, v78 quad_perm:[1,0,3,2] row_mask:0xf bank_mask:0xf bound_ctrl:1
	s_nop 1
	v_add_u32_dpp v78, v78, v78 quad_perm:[2,3,0,1] row_mask:0xf bank_mask:0xf bound_ctrl:1
	s_nop 1
	v_add_u32_dpp v78, v78, v78 row_half_mirror row_mask:0xf bank_mask:0xf bound_ctrl:1
	s_nop 1
	v_add_u32_dpp v78, v78, v78 row_mirror row_mask:0xf bank_mask:0xf bound_ctrl:1
	s_nop 0
	v_readlane_b32 s0, v78, 0
	v_readlane_b32 s1, v78, 16
	s_add_i32 s0, s1, s0
	v_readlane_b32 s1, v78, 32
	s_add_i32 s0, s0, s1
	v_readlane_b32 s1, v78, 48
	s_add_i32 s0, s0, s1
	s_cmpk_lt_i32 s0, 0x100
	s_cselect_b64 vcc, -1, 0
	s_addk_i32 s0, 0xff00
	s_cmp_lt_u32 s0, 17
	v_cndmask_b32_e32 v61, v77, v61, vcc
	s_cselect_b64 s[0:1], -1, 0
	v_subrev_co_u32_e32 v76, vcc, 1, v76
	s_or_b64 s[0:1], s[0:1], vcc
	s_andn2_b64 vcc, exec, s[0:1]
	s_cbranch_vccnz .LBB0_3987
	v_lshl_add_u32 v68, v60, 2, s5
	v_cmp_ge_u32_e32 vcc, v2, v61
	v_mov_b32_e32 v69, 0
	s_and_saveexec_b64 s[0:1], vcc
	v_mov_b32_e32 v69, 64
	ds_write_b32 v68, v2
	s_or_b64 exec, exec, s[0:1]
	v_cmp_ge_u32_e64 s[0:1], v1, v61
	s_and_saveexec_b64 s[6:7], s[0:1]
	v_lshl_add_u32 v69, v69, 2, v68
	ds_write_b32 v69, v1
	s_or_b64 exec, exec, s[6:7]
	v_cndmask_b32_e64 v69, 0, 1, vcc
	v_cndmask_b32_e64 v70, 0, 1, s[0:1]
	v_add_u32_e32 v69, v69, v70
	v_cmp_ge_u32_e32 vcc, v62, v61
	s_and_saveexec_b64 s[0:1], vcc
	v_lshl_add_u32 v70, v69, 8, v68
	ds_write_b32 v70, v62
	s_or_b64 exec, exec, s[0:1]
	v_cndmask_b32_e64 v70, 0, 1, vcc
	v_add_u32_e32 v69, v69, v70
	v_cmp_ge_u32_e32 vcc, v63, v61
	s_and_saveexec_b64 s[0:1], vcc
	v_lshl_add_u32 v70, v69, 8, v68
	ds_write_b32 v70, v63
	s_or_b64 exec, exec, s[0:1]
	v_cndmask_b32_e64 v70, 0, 1, vcc
	v_add_u32_e32 v69, v69, v70
	v_cmp_ge_u32_e32 vcc, v64, v61
	s_and_saveexec_b64 s[0:1], vcc
	v_lshl_add_u32 v70, v69, 8, v68
	ds_write_b32 v70, v64
	s_or_b64 exec, exec, s[0:1]
	v_cndmask_b32_e64 v70, 0, 1, vcc
	v_add_u32_e32 v69, v69, v70
	v_cmp_ge_u32_e32 vcc, v65, v61
	s_and_saveexec_b64 s[0:1], vcc
	v_lshl_add_u32 v70, v69, 8, v68
	ds_write_b32 v70, v65
	s_or_b64 exec, exec, s[0:1]
	v_cndmask_b32_e64 v70, 0, 1, vcc
	v_add_u32_e32 v69, v69, v70
	v_cmp_ge_u32_e32 vcc, v66, v61
	v_min_u32_e32 v70, 31, v69
	v_lshl_add_u32 v70, v70, 8, v68
	ds_write_b32 v70, v66
	v_addc_co_u32_e32 v69, vcc, 0, v69, vcc
	v_cmp_ge_u32_e32 vcc, v67, v61
	v_min_u32_e32 v70, 31, v69
	v_lshl_add_u32 v70, v70, 8, v68
	ds_write_b32 v70, v67
	v_addc_co_u32_e32 v69, vcc, 0, v69, vcc
	v_cmp_ge_u32_e32 vcc, v56, v61
	v_min_u32_e32 v70, 31, v69
	v_lshl_add_u32 v70, v70, 8, v68
	ds_write_b32 v70, v56
	v_addc_co_u32_e32 v69, vcc, 0, v69, vcc
	v_cmp_ge_u32_e32 vcc, v57, v61
	v_min_u32_e32 v70, 31, v69
	v_lshl_add_u32 v70, v70, 8, v68
	ds_write_b32 v70, v57
	v_addc_co_u32_e32 v69, vcc, 0, v69, vcc
	v_cmp_ge_u32_e32 vcc, v58, v61
	v_min_u32_e32 v70, 31, v69
	v_lshl_add_u32 v70, v70, 8, v68
	ds_write_b32 v70, v58
	v_addc_co_u32_e32 v69, vcc, 0, v69, vcc
	v_cmp_ge_u32_e32 vcc, v59, v61
	v_min_u32_e32 v70, 31, v69
	v_lshl_add_u32 v70, v70, 8, v68
	ds_write_b32 v70, v59
	v_addc_co_u32_e32 v69, vcc, 0, v69, vcc
	v_cmp_ge_u32_e32 vcc, v52, v61
	v_min_u32_e32 v70, 31, v69
	v_lshl_add_u32 v70, v70, 8, v68
	ds_write_b32 v70, v52
	v_addc_co_u32_e32 v69, vcc, 0, v69, vcc
	v_cmp_ge_u32_e32 vcc, v53, v61
	v_min_u32_e32 v70, 31, v69
	v_lshl_add_u32 v70, v70, 8, v68
	ds_write_b32 v70, v53
	v_addc_co_u32_e32 v69, vcc, 0, v69, vcc
	v_cmp_ge_u32_e32 vcc, v54, v61
	v_min_u32_e32 v70, 31, v69
	v_lshl_add_u32 v70, v70, 8, v68
	ds_write_b32 v70, v54
	v_addc_co_u32_e32 v69, vcc, 0, v69, vcc
	v_cmp_ge_u32_e32 vcc, v55, v61
	v_min_u32_e32 v70, 31, v69
	v_lshl_add_u32 v70, v70, 8, v68
	ds_write_b32 v70, v55
	v_addc_co_u32_e32 v69, vcc, 0, v69, vcc
	v_cmp_ge_u32_e32 vcc, v48, v61
	v_min_u32_e32 v70, 31, v69
	v_lshl_add_u32 v70, v70, 8, v68
	ds_write_b32 v70, v48
	v_addc_co_u32_e32 v69, vcc, 0, v69, vcc
	v_cmp_ge_u32_e32 vcc, v49, v61
	v_min_u32_e32 v70, 31, v69
	v_lshl_add_u32 v70, v70, 8, v68
	ds_write_b32 v70, v49
	v_addc_co_u32_e32 v69, vcc, 0, v69, vcc
	v_cmp_ge_u32_e32 vcc, v50, v61
	v_min_u32_e32 v70, 31, v69
	v_lshl_add_u32 v70, v70, 8, v68
	ds_write_b32 v70, v50
	v_addc_co_u32_e32 v69, vcc, 0, v69, vcc
	v_cmp_ge_u32_e32 vcc, v51, v61
	v_min_u32_e32 v70, 31, v69
	v_lshl_add_u32 v70, v70, 8, v68
	ds_write_b32 v70, v51
	v_addc_co_u32_e32 v69, vcc, 0, v69, vcc
	v_cmp_ge_u32_e32 vcc, v44, v61
	v_min_u32_e32 v70, 31, v69
	v_lshl_add_u32 v70, v70, 8, v68
	ds_write_b32 v70, v44
	v_addc_co_u32_e32 v69, vcc, 0, v69, vcc
	v_cmp_ge_u32_e32 vcc, v45, v61
	v_min_u32_e32 v70, 31, v69
	v_lshl_add_u32 v70, v70, 8, v68
	ds_write_b32 v70, v45
	v_addc_co_u32_e32 v69, vcc, 0, v69, vcc
	v_cmp_ge_u32_e32 vcc, v46, v61
	v_min_u32_e32 v70, 31, v69
	v_lshl_add_u32 v70, v70, 8, v68
	ds_write_b32 v70, v46
	v_addc_co_u32_e32 v69, vcc, 0, v69, vcc
	v_cmp_ge_u32_e32 vcc, v47, v61
	v_min_u32_e32 v70, 31, v69
	v_lshl_add_u32 v70, v70, 8, v68
	ds_write_b32 v70, v47
	v_addc_co_u32_e32 v69, vcc, 0, v69, vcc
; template <int NCH>
; __device__ __forceinline__ void dsa_topk_query(unsigned char* ws, const float* srow  , LAS unsigned* hist  , int t, int lane_in) {
;     ...
;             for (int c = 0; c < NCH; ++c) { const bool pr = u[c] >= Tl; if (pr) cb[((cl & 31) << 6) + lane] = u[c]; cl += pr ? 1 : 0; }
	v_cmp_ge_u32_e32 vcc, v40, v61
	v_min_u32_e32 v70, 31, v69
	v_lshl_add_u32 v70, v70, 8, v68
	ds_write_b32 v70, v40
	v_addc_co_u32_e32 v69, vcc, 0, v69, vcc
	v_cmp_ge_u32_e32 vcc, v41, v61
	v_min_u32_e32 v70, 31, v69
	v_lshl_add_u32 v70, v70, 8, v68
	ds_write_b32 v70, v41
	v_addc_co_u32_e32 v69, vcc, 0, v69, vcc
	v_cmp_ge_u32_e32 vcc, v42, v61
	v_min_u32_e32 v70, 31, v69
	v_lshl_add_u32 v70, v70, 8, v68
	ds_write_b32 v70, v42
	v_addc_co_u32_e32 v69, vcc, 0, v69, vcc
	v_cmp_ge_u32_e32 vcc, v43, v61
	v_min_u32_e32 v70, 31, v69
	v_lshl_add_u32 v70, v70, 8, v68
	ds_write_b32 v70, v43
	v_addc_co_u32_e32 v69, vcc, 0, v69, vcc
	v_cmp_ge_u32_e32 vcc, v36, v61
	v_min_u32_e32 v70, 31, v69
	v_lshl_add_u32 v70, v70, 8, v68
	ds_write_b32 v70, v36
	v_addc_co_u32_e32 v69, vcc, 0, v69, vcc
	v_cmp_ge_u32_e32 vcc, v37, v61
	v_min_u32_e32 v70, 31, v69
	v_lshl_add_u32 v70, v70, 8, v68
	ds_write_b32 v70, v37
	v_addc_co_u32_e32 v69, vcc, 0, v69, vcc
	v_cmp_ge_u32_e32 vcc, v38, v61
	v_min_u32_e32 v70, 31, v69
	v_lshl_add_u32 v70, v70, 8, v68
	ds_write_b32 v70, v38
	v_addc_co_u32_e32 v69, vcc, 0, v69, vcc
	v_cmp_ge_u32_e32 vcc, v39, v61
	v_min_u32_e32 v70, 31, v69
	v_lshl_add_u32 v70, v70, 8, v68
	ds_write_b32 v70, v39
	v_addc_co_u32_e32 v69, vcc, 0, v69, vcc
	v_cmp_ge_u32_e32 vcc, v32, v61
	v_min_u32_e32 v70, 31, v69
	v_lshl_add_u32 v70, v70, 8, v68
	ds_write_b32 v70, v32
	v_addc_co_u32_e32 v69, vcc, 0, v69, vcc
	v_cmp_ge_u32_e32 vcc, v33, v61
	v_min_u32_e32 v70, 31, v69
	v_lshl_add_u32 v70, v70, 8, v68
	ds_write_b32 v70, v33
	v_addc_co_u32_e32 v69, vcc, 0, v69, vcc
	v_cmp_ge_u32_e32 vcc, v34, v61
	v_min_u32_e32 v70, 31, v69
	v_lshl_add_u32 v70, v70, 8, v68
	ds_write_b32 v70, v34
	v_addc_co_u32_e32 v69, vcc, 0, v69, vcc
	v_cmp_ge_u32_e32 vcc, v35, v61
	v_min_u32_e32 v70, 31, v69
	v_lshl_add_u32 v70, v70, 8, v68
	ds_write_b32 v70, v35
	v_addc_co_u32_e32 v69, vcc, 0, v69, vcc
	v_cmp_ge_u32_e32 vcc, v28, v61
	v_min_u32_e32 v70, 31, v69
	v_lshl_add_u32 v70, v70, 8, v68
	ds_write_b32 v70, v28
	v_addc_co_u32_e32 v69, vcc, 0, v69, vcc
	v_cmp_ge_u32_e32 vcc, v29, v61
	v_min_u32_e32 v70, 31, v69
	v_lshl_add_u32 v70, v70, 8, v68
	ds_write_b32 v70, v29
	v_addc_co_u32_e32 v69, vcc, 0, v69, vcc
	v_cmp_ge_u32_e32 vcc, v30, v61
	v_min_u32_e32 v70, 31, v69
	v_lshl_add_u32 v70, v70, 8, v68
	ds_write_b32 v70, v30
	v_addc_co_u32_e32 v69, vcc, 0, v69, vcc
	v_cmp_ge_u32_e32 vcc, v31, v61
	v_min_u32_e32 v70, 31, v69
	v_lshl_add_u32 v70, v70, 8, v68
	ds_write_b32 v70, v31
	v_addc_co_u32_e32 v69, vcc, 0, v69, vcc
	v_cmp_ge_u32_e32 vcc, v24, v61
	v_min_u32_e32 v70, 31, v69
	v_lshl_add_u32 v70, v70, 8, v68
	ds_write_b32 v70, v24
	v_addc_co_u32_e32 v69, vcc, 0, v69, vcc
	v_cmp_ge_u32_e32 vcc, v25, v61
	v_min_u32_e32 v70, 31, v69
	v_lshl_add_u32 v70, v70, 8, v68
	ds_write_b32 v70, v25
	v_addc_co_u32_e32 v69, vcc, 0, v69, vcc
	v_cmp_ge_u32_e32 vcc, v26, v61
	v_min_u32_e32 v70, 31, v69
	v_lshl_add_u32 v70, v70, 8, v68
	ds_write_b32 v70, v26
	v_addc_co_u32_e32 v69, vcc, 0, v69, vcc
	v_cmp_ge_u32_e32 vcc, v27, v61
	v_min_u32_e32 v70, 31, v69
	v_lshl_add_u32 v70, v70, 8, v68
	ds_write_b32 v70, v27
	v_addc_co_u32_e32 v69, vcc, 0, v69, vcc
	v_cmp_ge_u32_e32 vcc, v16, v61
	v_min_u32_e32 v70, 31, v69
	v_lshl_add_u32 v70, v70, 8, v68
	ds_write_b32 v70, v16
	v_addc_co_u32_e32 v69, vcc, 0, v69, vcc
	v_cmp_ge_u32_e32 vcc, v17, v61
	v_min_u32_e32 v70, 31, v69
	v_lshl_add_u32 v70, v70, 8, v68
	ds_write_b32 v70, v17
	v_addc_co_u32_e32 v69, vcc, 0, v69, vcc
	v_cmp_ge_u32_e32 vcc, v18, v61
	v_min_u32_e32 v70, 31, v69
	v_lshl_add_u32 v70, v70, 8, v68
	ds_write_b32 v70, v18
	v_addc_co_u32_e32 v69, vcc, 0, v69, vcc
	v_cmp_ge_u32_e32 vcc, v19, v61
	v_min_u32_e32 v70, 31, v69
	v_lshl_add_u32 v70, v70, 8, v68
	ds_write_b32 v70, v19
	v_addc_co_u32_e32 v69, vcc, 0, v69, vcc
	v_cmp_ge_u32_e32 vcc, v20, v61
	v_min_u32_e32 v70, 31, v69
	v_lshl_add_u32 v70, v70, 8, v68
	ds_write_b32 v70, v20
	v_addc_co_u32_e32 v69, vcc, 0, v69, vcc
	v_cmp_ge_u32_e32 vcc, v21, v61
	v_min_u32_e32 v70, 31, v69
	v_lshl_add_u32 v70, v70, 8, v68
	ds_write_b32 v70, v21
	v_addc_co_u32_e32 v69, vcc, 0, v69, vcc
	v_cmp_ge_u32_e32 vcc, v22, v61
	v_min_u32_e32 v70, 31, v69
	v_lshl_add_u32 v70, v70, 8, v68
	ds_write_b32 v70, v22
	v_addc_co_u32_e32 v69, vcc, 0, v69, vcc
	v_cmp_ge_u32_e32 vcc, v23, v61
	v_min_u32_e32 v70, 31, v69
	v_lshl_add_u32 v70, v70, 8, v68
	ds_write_b32 v70, v23
	v_addc_co_u32_e32 v69, vcc, 0, v69, vcc
	v_cmp_ge_u32_e32 vcc, v12, v61
	v_min_u32_e32 v70, 31, v69
	v_lshl_add_u32 v70, v70, 8, v68
	ds_write_b32 v70, v12
	v_addc_co_u32_e32 v69, vcc, 0, v69, vcc
	v_cmp_ge_u32_e32 vcc, v13, v61
	v_min_u32_e32 v70, 31, v69
	v_lshl_add_u32 v70, v70, 8, v68
	ds_write_b32 v70, v13
	v_addc_co_u32_e32 v69, vcc, 0, v69, vcc
	v_cmp_ge_u32_e32 vcc, v14, v61
; template <int NCH>
; __device__ __forceinline__ void dsa_topk_query(unsigned char* ws, const float* srow  , LAS unsigned* hist  , int t, int lane_in) {
;     ...
;             for (int c = 0; c < NCH; ++c) { const bool pr = u[c] >= Tl; if (pr) cb[((cl & 31) << 6) + lane] = u[c]; cl += pr ? 1 : 0; }
;             if (wave_max_i(cl) <= 16) {
;                 unsigned k[16];
; #pragma unroll
;                 for (int i = 0; i < 16; ++i) { k[i] = 0u; if (i < cl) k[i] = cb[(i << 6) + lane]; }
	v_min_u32_e32 v70, 31, v69
	v_lshl_add_u32 v70, v70, 8, v68
	ds_write_b32 v70, v14
	v_addc_co_u32_e32 v69, vcc, 0, v69, vcc
	v_cmp_ge_u32_e32 vcc, v15, v61
	v_min_u32_e32 v70, 31, v69
	v_lshl_add_u32 v70, v70, 8, v68
	ds_write_b32 v70, v15
	v_addc_co_u32_e32 v69, vcc, 0, v69, vcc
	v_cmp_ge_u32_e32 vcc, v8, v61
	v_min_u32_e32 v70, 31, v69
	v_lshl_add_u32 v70, v70, 8, v68
	ds_write_b32 v70, v8
	v_addc_co_u32_e32 v69, vcc, 0, v69, vcc
	v_cmp_ge_u32_e32 vcc, v9, v61
	v_min_u32_e32 v70, 31, v69
	v_lshl_add_u32 v70, v70, 8, v68
	ds_write_b32 v70, v9
	v_addc_co_u32_e32 v69, vcc, 0, v69, vcc
	v_cmp_ge_u32_e32 vcc, v10, v61
	v_min_u32_e32 v70, 31, v69
	v_lshl_add_u32 v70, v70, 8, v68
	ds_write_b32 v70, v10
	v_addc_co_u32_e32 v69, vcc, 0, v69, vcc
	v_cmp_ge_u32_e32 vcc, v11, v61
	v_min_u32_e32 v70, 31, v69
	v_lshl_add_u32 v70, v70, 8, v68
	ds_write_b32 v70, v11
	v_addc_co_u32_e32 v69, vcc, 0, v69, vcc
	v_cmp_ge_u32_e32 vcc, v4, v61
	v_min_u32_e32 v70, 31, v69
	v_lshl_add_u32 v70, v70, 8, v68
	ds_write_b32 v70, v4
	v_addc_co_u32_e32 v69, vcc, 0, v69, vcc
	v_cmp_ge_u32_e32 vcc, v5, v61
	v_min_u32_e32 v70, 31, v69
	v_lshl_add_u32 v70, v70, 8, v68
	ds_write_b32 v70, v5
	v_addc_co_u32_e32 v69, vcc, 0, v69, vcc
	v_cmp_ge_u32_e32 vcc, v6, v61
	v_min_u32_e32 v70, 31, v69
	v_lshl_add_u32 v70, v70, 8, v68
	ds_write_b32 v70, v6
	v_addc_co_u32_e32 v69, vcc, 0, v69, vcc
	v_cmp_ge_u32_e32 vcc, v7, v61
	s_and_saveexec_b64 s[0:1], vcc
	v_lshlrev_b32_e32 v70, 8, v69
	v_and_b32_e32 v70, 0x1f00, v70
	v_add_u32_e32 v70, v68, v70
	ds_write_b32 v70, v7
	s_or_b64 exec, exec, s[0:1]
	v_cndmask_b32_e64 v70, 0, 1, vcc
	v_add_u32_e32 v74, v69, v70
	s_mov_b32 s10, 0
	s_nop 0
	v_max_i32_dpp v69, v74, v74 quad_perm:[1,0,3,2] row_mask:0xf bank_mask:0xf bound_ctrl:1
	s_nop 1
	v_max_i32_dpp v69, v69, v69 quad_perm:[2,3,0,1] row_mask:0xf bank_mask:0xf bound_ctrl:1
	s_nop 1
	v_max_i32_dpp v69, v69, v69 row_half_mirror row_mask:0xf bank_mask:0xf bound_ctrl:1
	s_nop 1
	v_max_i32_dpp v69, v69, v69 row_mirror row_mask:0xf bank_mask:0xf bound_ctrl:1
	s_nop 0
	v_readlane_b32 s2, v69, 32
	v_readlane_b32 s6, v69, 48
	v_readlane_b32 s1, v69, 16
	s_max_i32 s2, s2, s6
	v_readlane_b32 s0, v69, 0
	v_mov_b32_e32 v69, s1
	v_mov_b32_e32 v70, s2
	v_max3_i32 v69, s0, v69, v70
	v_cmp_lt_i32_e64 s[0:1], 16, v69
	s_and_b64 vcc, exec, s[0:1]
	s_cbranch_vccnz .LBB0_4153
	v_mov_b32_e32 v69, 0
	v_cmp_ne_u32_e32 vcc, 0, v74
	v_mov_b32_e32 v70, 0
	s_and_saveexec_b64 s[6:7], vcc
	ds_read_b32 v70, v68
	s_or_b64 exec, exec, s[6:7]
	v_cmp_lt_u32_e32 vcc, 1, v74
	s_and_saveexec_b64 s[6:7], vcc
	ds_read_b32 v69, v68 offset:256
	s_or_b64 exec, exec, s[6:7]
	v_cmp_lt_u32_e32 vcc, 2, v74
	v_mov_b32_e32 v71, 0
	v_mov_b32_e32 v72, 0
	s_and_saveexec_b64 s[6:7], vcc
	ds_read_b32 v72, v68 offset:512
	s_or_b64 exec, exec, s[6:7]
	v_cmp_lt_u32_e32 vcc, 3, v74
	s_and_saveexec_b64 s[6:7], vcc
	ds_read_b32 v71, v68 offset:768
	s_or_b64 exec, exec, s[6:7]
	v_cmp_lt_u32_e32 vcc, 4, v74
	v_mov_b32_e32 v73, 0
	v_mov_b32_e32 v75, 0
	s_and_saveexec_b64 s[6:7], vcc
	ds_read_b32 v75, v68 offset:1024
	s_or_b64 exec, exec, s[6:7]
	v_cmp_lt_u32_e32 vcc, 5, v74
	s_and_saveexec_b64 s[6:7], vcc
	ds_read_b32 v73, v68 offset:1280
	s_or_b64 exec, exec, s[6:7]
	v_cmp_lt_u32_e32 vcc, 6, v74
	v_mov_b32_e32 v76, 0
	v_mov_b32_e32 v77, 0
	s_and_saveexec_b64 s[6:7], vcc
	ds_read_b32 v77, v68 offset:1536
	s_or_b64 exec, exec, s[6:7]
	v_cmp_lt_u32_e32 vcc, 7, v74
	s_and_saveexec_b64 s[6:7], vcc
	ds_read_b32 v76, v68 offset:1792
	s_or_b64 exec, exec, s[6:7]
	v_cmp_lt_u32_e32 vcc, 8, v74
	v_mov_b32_e32 v78, 0
	v_mov_b32_e32 v79, 0
	s_and_saveexec_b64 s[6:7], vcc
	ds_read_b32 v79, v68 offset:2048
	s_or_b64 exec, exec, s[6:7]
	v_cmp_lt_u32_e32 vcc, 9, v74
	s_and_saveexec_b64 s[6:7], vcc
	ds_read_b32 v78, v68 offset:2304
	s_or_b64 exec, exec, s[6:7]
	v_cmp_lt_u32_e32 vcc, 10, v74
	v_mov_b32_e32 v80, 0
	v_mov_b32_e32 v81, 0
	s_and_saveexec_b64 s[6:7], vcc
	ds_read_b32 v81, v68 offset:2560
	s_or_b64 exec, exec, s[6:7]
	v_cmp_lt_u32_e32 vcc, 11, v74
	s_and_saveexec_b64 s[6:7], vcc
	ds_read_b32 v80, v68 offset:2816
	s_or_b64 exec, exec, s[6:7]
	v_cmp_lt_u32_e32 vcc, 12, v74
	v_mov_b32_e32 v82, 0
	v_mov_b32_e32 v83, 0
	s_and_saveexec_b64 s[6:7], vcc
	ds_read_b32 v83, v68 offset:3072
	s_or_b64 exec, exec, s[6:7]
	v_cmp_lt_u32_e32 vcc, 13, v74
	s_and_saveexec_b64 s[6:7], vcc
	ds_read_b32 v82, v68 offset:3328
	s_or_b64 exec, exec, s[6:7]
	v_cmp_lt_u32_e32 vcc, 14, v74
	v_mov_b32_e32 v84, 0
	v_mov_b32_e32 v85, 0
	s_and_saveexec_b64 s[6:7], vcc
	ds_read_b32 v85, v68 offset:3584
	s_or_b64 exec, exec, s[6:7]
	v_cmp_lt_u32_e32 vcc, 15, v74
	s_and_saveexec_b64 s[6:7], vcc
	ds_read_b32 v84, v68 offset:3840
	s_or_b64 exec, exec, s[6:7]
	v_mov_b32_e32 v68, 31
	v_mov_b32_e32 v74, 0
